# EpiUp: drop the 1-state pads hipcc puts after default-op_sel packed-f32 ops (it does not pad the op_sel_hi:[0,1] forms); plus d4 edits
# speedup vs baseline: 1.0044x; 1.0024x over previous
; __device__ __forceinline__ float row_rstd(const float* slots, int row, int ncols, float eps) { const f32x4 v = *(const f32x4*)(slots + (size_t)row * 4); return rsqrtf(((v[0] + v[1]) + (v[2] + v[3])) * (1.0f / ncols) + eps); }
;     __device__ __forceinline__ void operator()(const f32x4 (&acc_)[2][2][4][2], const Unit& u, int wr, int wc, int fr, int fq) const {
;     ...
;         { const int tix = (wr * 4 + wc) * 64 + fq * 16 + fr, wi = tix >> 7, ci = tix & 127;
;           xg[1024 + tix] = wi < 3 ? cw[wi * dff + u.pn * 128 + ci] : cb[u.pn * 128 + ci];
;           if (tix < 256) { int t = a_tok0(u.pm) + tix; t = t < 0 ? 0 : (t > Mtok - 1 ? Mtok - 1 : t); xg[1536 + tix] = row_rstd(slots, t, 1024, 1e-6f); } }
.LBB0_655:
	s_or_b64 exec, exec, s[44:45]
	s_lshl_b32 s1, s82, 7
	v_or_b32_e32 v46, s1, v220
	v_add_u32_e32 v47, s1, v230
	v_cndmask_b32_e64 v46, v46, v47, s[2:3]
	v_ashrrev_i32_e32 v47, 31, v46
	v_lshl_add_u64 v[46:47], v[46:47], 2, s[52:53]
	global_load_dword v46, v[46:47], off
	s_mul_i32 s33, s0, 0xfe
	s_add_i32 s33, s33, -1
	s_waitcnt vmcnt(0)
	ds_write_b32 v231, v46 offset:4096
	s_and_saveexec_b64 s[44:45], s[4:5]
	s_cbranch_execz .LBB0_657
	v_add_u32_e32 v46, s33, v219
	v_mov_b32_e32 v47, 0x3fff
	v_med3_i32 v46, v46, 0, v47
	v_readlane_b32 s18, v252, 36
	v_lshlrev_b32_e32 v46, 4, v46
	v_readlane_b32 s19, v252, 37
	s_mov_b32 s0, 0x800000
	s_nop 3
	global_load_dwordx4 v[46:49], v46, s[18:19]
	s_waitcnt vmcnt(0)
	v_mov_b32_e32 v50, v47
	v_mov_b32_e32 v51, v48
	v_mov_b32_e32 v47, v49
	v_pk_add_f32 v[46:47], v[50:51], v[46:47]
	v_add_f32_e32 v46, v46, v47
	v_mov_b32_e32 v47, 0x358637bd
	v_fmamk_f32 v46, v46, 0x3a800000, v47
	v_mul_f32_e32 v47, 0x4b800000, v46
	v_cmp_gt_f32_e32 vcc, s0, v46
	s_nop 1
	v_cndmask_b32_e32 v46, v46, v47, vcc
	v_rsq_f32_e32 v46, v46
	s_nop 0
	v_mul_f32_e32 v47, 0x45800000, v46
	v_cndmask_b32_e32 v46, v46, v47, vcc
	ds_write_b32 v231, v46 offset:6144

;     __device__ __forceinline__ void operator()(const f32x4 (&acc_)[2][2][4][2], const Unit& u, int wr, int wc, int fr, int fq) const {
;     ...
;                 const int lr = ai * HALF + wr * 64 + m * 16 + fr, t = a_tok0(u.pm) + lr, tq = t & (Tg - 1);
;                 const float mp = tq == 0 ? 0.f : 1.f, mn = tq == Tg - 1 ? 0.f : 1.f;
;                 u32x4 ov;
; #pragma unroll
;                 for (int n = 0; n < 2; ++n) {
;                     const f32x4 w0 = *(const PG8_LAS f32x4*)(wl + jj + 4 * n), w1 = *(const PG8_LAS f32x4*)(wl + 128 + jj + 4 * n), w2 = *(const PG8_LAS f32x4*)(wl + 256 + jj + 4 * n), bb = *(const PG8_LAS f32x4*)(wl + 384 + jj + 4 * n);
;                     f32x4 bp = {0.f, 0.f, 0.f, 0.f}, bn = {0.f, 0.f, 0.f, 0.f};
;                     if (m == 0 && sp >= 0) bp = *(const PG8_LAS f32x4*)(xg + sp * 128 + jj + 4 * n) * xg[1536 + ai * HALF + wr * 64 - 1];
;                     if (m == 3 && sn >= 0) bn = *(const PG8_LAS f32x4*)(xg + sn * 128 + jj + 4 * n) * xg[1536 + ai * HALF + wr * 64 + 64];
; #pragma unroll
;                     for (int eh = 0; eh < 2; ++eh) { v2f gv, p, q, up;
; #pragma unroll
;                         for (int k = 0; k < 2; ++k) { const int e = 2 * eh + k; const float g0 = acc[ai][0][m][n][e];
;                             const float pa = m > 0 ? dpp_ror1(acc[ai][0][m > 0 ? m - 1 : 0][n][e]) : bp[e];
;                             const float qa = m < 3 ? dpp_ror15(acc[ai][0][m < 3 ? m + 1 : 3][n][e]) : bn[e];
;                             gv[k] = g0; up[k] = acc[ai][1][m][n][e];
;                             p[k] = __builtin_bit_cast(float, __builtin_amdgcn_update_dpp(__builtin_bit_cast(int, pa), __builtin_bit_cast(int, g0), 0x111, 0xf, 0xf, false));
;                             q[k] = __builtin_bit_cast(float, __builtin_amdgcn_update_dpp(__builtin_bit_cast(int, qa), __builtin_bit_cast(int, g0), 0x101, 0xf, 0xf, false)); }
;                         const v2f a0 = (v2f){w0[2 * eh], w0[2 * eh + 1]} * mp, a1 = (v2f){w1[2 * eh], w1[2 * eh + 1]}, a2 = (v2f){w2[2 * eh], w2[2 * eh + 1]} * mn, ab = (v2f){bb[2 * eh], bb[2 * eh + 1]};
;                         const v2f x = a0 * p + (a1 * gv + (a2 * q + ab));
;                         const v2f arg = x * ((x * x) * (-0.10294324f) + (-2.3022082f));
;                         v2f ex; ex[0] = __builtin_amdgcn_exp2f(arg[0]); ex[1] = __builtin_amdgcn_exp2f(arg[1]);
.LBB0_661:
	v_mov_b32_e32 v199, v198
	v_mov_b32_e32 v189, v188
	v_mov_b32_e32 v210, v198
	v_mov_b32_e32 v211, v198
	v_pk_mul_f32 v[196:197], v[146:147], v[198:199]
	v_mov_b32_e32 v146, v188
	v_mov_b32_e32 v147, v188
	v_add_u32_e32 v181, s33, v5
	v_pk_mul_f32 v[194:195], v[148:149], v[210:211]
	v_pk_mul_f32 v[146:147], v[156:157], v[146:147]
	v_pk_mul_f32 v[148:149], v[154:155], v[188:189]
	v_mov_b32_e32 v155, v0
	v_or_b32_e32 v176, s1, v218
	v_mov_b32_dpp v156, v148 row_ror:15 row_mask:0xf bank_mask:0xf
	v_mov_b32_dpp v157, v149 row_ror:15 row_mask:0xf bank_mask:0xf
	v_mov_b32_dpp v154, v146 row_ror:15 row_mask:0xf bank_mask:0xf
	v_mov_b32_dpp v155, v147 row_ror:15 row_mask:0xf bank_mask:0xf
	v_cmp_gt_i32_e32 vcc, s26, v181
	v_ashrrev_i32_e32 v177, 31, v176
	v_mov_b32_dpp v200, v196 row_shr:1 row_mask:0xf bank_mask:0xf
	v_mov_b32_dpp v156, v196 row_shl:1 row_mask:0xf bank_mask:0xf
	v_mov_b32_dpp v201, v197 row_shr:1 row_mask:0xf bank_mask:0xf
	v_mov_b32_dpp v157, v197 row_shl:1 row_mask:0xf bank_mask:0xf
	v_mov_b32_dpp v202, v194 row_shr:1 row_mask:0xf bank_mask:0xf
	v_mov_b32_dpp v154, v194 row_shl:1 row_mask:0xf bank_mask:0xf
	v_mov_b32_dpp v203, v195 row_shr:1 row_mask:0xf bank_mask:0xf
	v_mov_b32_dpp v155, v195 row_shl:1 row_mask:0xf bank_mask:0xf
	s_and_b64 s[0:1], s[6:7], vcc
	s_and_saveexec_b64 s[46:47], s[0:1]
	s_cbranch_execz .LBB0_663
	v_and_b32_e32 v161, s34, v181
	v_cmp_eq_u32_e32 vcc, 0, v161
	s_mov_b32 s0, 0xc0135761
	v_pk_mul_f32 v[150:151], v[150:151], v[198:199]
	v_cndmask_b32_e64 v160, 1.0, 0, vcc
	v_cmp_eq_u32_e32 vcc, s34, v161
	s_waitcnt lgkmcnt(7)
	v_pk_mul_f32 v[244:245], v[160:161], v[50:51] op_sel_hi:[0,1]
	v_pk_mul_f32 v[152:153], v[152:153], v[210:211]
	v_cndmask_b32_e64 v214, 1.0, 0, vcc
	s_waitcnt lgkmcnt(5)
	v_pk_mul_f32 v[246:247], v[214:215], v[54:55] op_sel_hi:[0,1]
	s_waitcnt lgkmcnt(4)
	v_pk_fma_f32 v[212:213], v[246:247], v[212:213], v[58:59]
	v_pk_mul_f32 v[142:143], v[142:143], v[198:199]
	v_pk_fma_f32 v[212:213], v[192:193], v[46:47], v[212:213]
	s_waitcnt lgkmcnt(1)
	v_pk_mul_f32 v[198:199], v[214:215], v[70:71] op_sel_hi:[0,1]
	v_pk_fma_f32 v[208:209], v[244:245], v[208:209], v[212:213]
	v_mov_b64_e32 v[244:245], s[0:1]
	v_pk_mul_f32 v[212:213], v[208:209], v[208:209]
	s_mov_b32 s0, 0x3dd2d3e8
	v_pk_fma_f32 v[212:213], v[212:213], s[0:1], v[244:245] op_sel_hi:[1,0,0] neg_lo:[1,0,0] neg_hi:[1,0,0]
	s_waitcnt lgkmcnt(0)
	v_pk_fma_f32 v[156:157], v[198:199], v[156:157], v[66:67]
	v_pk_mul_f32 v[212:213], v[208:209], v[212:213]
	v_pk_fma_f32 v[156:157], v[196:197], v[62:63], v[156:157]
	v_exp_f32_e32 v212, v212
	v_exp_f32_e32 v213, v213
	v_pk_mul_f32 v[144:145], v[144:145], v[210:211]
	v_pk_add_f32 v[212:213], v[212:213], 1.0 op_sel_hi:[1,0]
	v_rcp_f32_e32 v212, v212
	v_rcp_f32_e32 v213, v213
	s_nop 0
	v_pk_mul_f32 v[208:209], v[208:209], v[212:213]
	v_pk_mul_f32 v[212:213], v[214:215], v[56:57] op_sel_hi:[0,1]
	v_pk_fma_f32 v[206:207], v[212:213], v[206:207], v[60:61]
	v_pk_mul_f32 v[150:151], v[150:151], v[208:209]
	v_pk_mul_f32 v[208:209], v[160:161], v[52:53] op_sel_hi:[0,1]
	v_pk_fma_f32 v[206:207], v[190:191], v[48:49], v[206:207]
	v_cvt_pk_bf16_f32 v150, v150, v151
	v_pk_fma_f32 v[204:205], v[208:209], v[204:205], v[206:207]
	v_pk_mul_f32 v[206:207], v[204:205], v[204:205]
	v_pk_fma_f32 v[206:207], v[206:207], s[0:1], v[244:245] op_sel_hi:[1,0,0] neg_lo:[1,0,0] neg_hi:[1,0,0]
	v_pk_mul_f32 v[206:207], v[204:205], v[206:207]
	v_exp_f32_e32 v206, v206
	v_exp_f32_e32 v207, v207
	s_nop 0
	v_pk_add_f32 v[206:207], v[206:207], 1.0 op_sel_hi:[1,0]
	v_rcp_f32_e32 v206, v206
	v_rcp_f32_e32 v207, v207
	s_nop 0
	v_pk_mul_f32 v[204:205], v[204:205], v[206:207]
	v_pk_mul_f32 v[152:153], v[152:153], v[204:205]
	v_cvt_pk_bf16_f32 v151, v152, v153
	v_pk_mul_f32 v[152:153], v[160:161], v[74:75] op_sel_hi:[0,1]
	v_pk_fma_f32 v[152:153], v[152:153], v[200:201], v[156:157]
	v_pk_mul_f32 v[156:157], v[152:153], v[152:153]
	v_pk_fma_f32 v[156:157], v[156:157], s[0:1], v[244:245] op_sel_hi:[1,0,0] neg_lo:[1,0,0] neg_hi:[1,0,0]
	v_pk_mul_f32 v[156:157], v[152:153], v[156:157]
	v_exp_f32_e32 v156, v156
	v_exp_f32_e32 v157, v157
	s_nop 0
	v_pk_add_f32 v[156:157], v[156:157], 1.0 op_sel_hi:[1,0]
	v_rcp_f32_e32 v156, v156
	v_rcp_f32_e32 v157, v157
	s_nop 0
	v_pk_mul_f32 v[152:153], v[152:153], v[156:157]
	v_pk_mul_f32 v[156:157], v[214:215], v[72:73] op_sel_hi:[0,1]
	v_pk_mul_f32 v[142:143], v[142:143], v[152:153]
	v_pk_fma_f32 v[154:155], v[156:157], v[154:155], v[68:69]
	v_cvt_pk_bf16_f32 v152, v142, v143
	v_pk_mul_f32 v[142:143], v[160:161], v[76:77] op_sel_hi:[0,1]
	v_pk_fma_f32 v[154:155], v[194:195], v[64:65], v[154:155]
	v_pk_fma_f32 v[142:143], v[142:143], v[202:203], v[154:155]
	v_pk_mul_f32 v[154:155], v[142:143], v[142:143]
	v_pk_fma_f32 v[154:155], v[154:155], s[0:1], v[244:245] op_sel_hi:[1,0,0] neg_lo:[1,0,0] neg_hi:[1,0,0]
	v_pk_mul_f32 v[154:155], v[142:143], v[154:155]
	v_exp_f32_e32 v154, v154
	v_exp_f32_e32 v155, v155
	s_nop 0
	v_pk_add_f32 v[154:155], v[154:155], 1.0 op_sel_hi:[1,0]
	v_rcp_f32_e32 v154, v154
	v_rcp_f32_e32 v155, v155
	s_nop 0
	v_pk_mul_f32 v[142:143], v[142:143], v[154:155]
	v_pk_mul_f32 v[142:143], v[144:145], v[142:143]
	v_cvt_pk_bf16_f32 v153, v142, v143
	v_mov_b64_e32 v[142:143], s[18:19]
	v_mad_i64_i32 v[142:143], s[0:1], v181, s27, v[142:143]
	v_lshl_add_u64 v[142:143], v[176:177], 1, v[142:143]
	global_store_dwordx4 v[142:143], v[150:153], off
; #define PG8_LAS __attribute__((address_space(3)))
;     __device__ __forceinline__ void operator()(const f32x4 (&acc_)[2][2][4][2], const Unit& u, int wr, int wc, int fr, int fq) const {
;     ...
;             for (int m = 0; m < 4; ++m) { const float r = xg[1536 + ai * HALF + wr * 64 + m * 16 + fr];
; #pragma unroll
;                 for (int bj = 0; bj < 2; ++bj)
; #pragma unroll
;                     for (int n = 0; n < 2; ++n) acc[ai][bj][m][n] *= r; }
;         typedef float v2f __attribute__((ext_vector_type(2)));
;         const PG8_LAS float* wl = xg + 1024;
; #pragma unroll
;         for (int ai = 0; ai < 2; ++ai) {
;             const int sp = wr == 1 ? ((ai * 2 + 0) * 2 + 1) : (ai == 1 ? ((0 * 2 + 1) * 2 + 1) : -1);
;             const int sn = wr == 0 ? ((ai * 2 + 1) * 2 + 0) : (ai == 0 ? ((1 * 2 + 0) * 2 + 0) : -1);
; #pragma unroll
;             for (int m = 0; m < 4; ++m) {
;                 const int lr = ai * HALF + wr * 64 + m * 16 + fr, t = a_tok0(u.pm) + lr, tq = t & (Tg - 1);
;                 const float mp = tq == 0 ? 0.f : 1.f, mn = tq == Tg - 1 ? 0.f : 1.f;
;                 u32x4 ov;
; #pragma unroll
;                 for (int n = 0; n < 2; ++n) {
;                     const f32x4 w0 = *(const PG8_LAS f32x4*)(wl + jj + 4 * n), w1 = *(const PG8_LAS f32x4*)(wl + 128 + jj + 4 * n), w2 = *(const PG8_LAS f32x4*)(wl + 256 + jj + 4 * n), bb = *(const PG8_LAS f32x4*)(wl + 384 + jj + 4 * n);
;                     f32x4 bp = {0.f, 0.f, 0.f, 0.f}, bn = {0.f, 0.f, 0.f, 0.f};
;                     if (m == 0 && sp >= 0) bp = *(const PG8_LAS f32x4*)(xg + sp * 128 + jj + 4 * n) * xg[1536 + ai * HALF + wr * 64 - 1];
;                     if (m == 3 && sn >= 0) bn = *(const PG8_LAS f32x4*)(xg + sn * 128 + jj + 4 * n) * xg[1536 + ai * HALF + wr * 64 + 64];
; #pragma unroll
;                     for (int eh = 0; eh < 2; ++eh) { v2f gv, p, q, up;
; #pragma unroll
;                         for (int k = 0; k < 2; ++k) { const int e = 2 * eh + k; const float g0 = acc[ai][0][m][n][e];
;                             const float pa = m > 0 ? dpp_ror1(acc[ai][0][m > 0 ? m - 1 : 0][n][e]) : bp[e];
;                             const float qa = m < 3 ? dpp_ror15(acc[ai][0][m < 3 ? m + 1 : 3][n][e]) : bn[e];
;                             gv[k] = g0; up[k] = acc[ai][1][m][n][e];
.LBB0_663:
	s_or_b64 exec, exec, s[46:47]
	v_pk_mul_f32 v[140:141], v[140:141], v[182:183] op_sel_hi:[1,0]
	v_pk_mul_f32 v[138:139], v[138:139], v[182:183] op_sel_hi:[1,0]
	v_pk_mul_f32 v[136:137], v[136:137], v[182:183] op_sel_hi:[1,0]
	v_pk_mul_f32 v[134:135], v[134:135], v[182:183] op_sel_hi:[1,0]
	v_add_u32_e32 v181, s33, v221
	v_mov_b32_dpp v198, v192 row_ror:1 row_mask:0xf bank_mask:0xf
	v_mov_b32_dpp v199, v193 row_ror:1 row_mask:0xf bank_mask:0xf
	v_mov_b32_dpp v192, v138 row_ror:15 row_mask:0xf bank_mask:0xf
	v_mov_b32_dpp v193, v139 row_ror:15 row_mask:0xf bank_mask:0xf
	v_mov_b32_dpp v154, v190 row_ror:1 row_mask:0xf bank_mask:0xf
	v_mov_b32_dpp v156, v140 row_ror:15 row_mask:0xf bank_mask:0xf
	v_mov_b32_dpp v155, v191 row_ror:1 row_mask:0xf bank_mask:0xf
	v_mov_b32_dpp v157, v141 row_ror:15 row_mask:0xf bank_mask:0xf
	v_mov_b32_dpp v150, v196 row_ror:1 row_mask:0xf bank_mask:0xf
	v_mov_b32_dpp v152, v134 row_ror:15 row_mask:0xf bank_mask:0xf
	v_mov_b32_dpp v151, v197 row_ror:1 row_mask:0xf bank_mask:0xf
	v_mov_b32_dpp v153, v135 row_ror:15 row_mask:0xf bank_mask:0xf
	v_mov_b32_dpp v142, v194 row_ror:1 row_mask:0xf bank_mask:0xf
	v_mov_b32_dpp v144, v136 row_ror:15 row_mask:0xf bank_mask:0xf
	v_mov_b32_dpp v143, v195 row_ror:1 row_mask:0xf bank_mask:0xf
	v_mov_b32_dpp v145, v137 row_ror:15 row_mask:0xf bank_mask:0xf
	v_cmp_gt_i32_e32 vcc, s26, v181
	v_mov_b32_dpp v198, v186 row_shr:1 row_mask:0xf bank_mask:0xf
	v_mov_b32_dpp v192, v186 row_shl:1 row_mask:0xf bank_mask:0xf
	v_mov_b32_dpp v199, v187 row_shr:1 row_mask:0xf bank_mask:0xf
	v_mov_b32_dpp v193, v187 row_shl:1 row_mask:0xf bank_mask:0xf
	v_mov_b32_dpp v154, v184 row_shr:1 row_mask:0xf bank_mask:0xf
	v_mov_b32_dpp v156, v184 row_shl:1 row_mask:0xf bank_mask:0xf
	v_mov_b32_dpp v155, v185 row_shr:1 row_mask:0xf bank_mask:0xf
	v_mov_b32_dpp v157, v185 row_shl:1 row_mask:0xf bank_mask:0xf
	v_mov_b32_dpp v150, v148 row_shr:1 row_mask:0xf bank_mask:0xf
	v_mov_b32_dpp v152, v148 row_shl:1 row_mask:0xf bank_mask:0xf
	v_mov_b32_dpp v151, v149 row_shr:1 row_mask:0xf bank_mask:0xf
	v_mov_b32_dpp v153, v149 row_shl:1 row_mask:0xf bank_mask:0xf
	v_mov_b32_dpp v142, v146 row_shr:1 row_mask:0xf bank_mask:0xf
	v_mov_b32_dpp v144, v146 row_shl:1 row_mask:0xf bank_mask:0xf
	v_mov_b32_dpp v143, v147 row_shr:1 row_mask:0xf bank_mask:0xf
	v_mov_b32_dpp v145, v147 row_shl:1 row_mask:0xf bank_mask:0xf
	s_and_b64 s[0:1], s[8:9], vcc
	s_and_saveexec_b64 s[46:47], s[0:1]
	s_cbranch_execz .LBB0_665
	v_and_b32_e32 v183, s34, v181
	v_mov_b32_e32 v160, v188
	v_mov_b32_e32 v161, v188
	v_cmp_eq_u32_e32 vcc, 0, v183
	v_pk_mul_f32 v[132:133], v[132:133], v[160:161]
	v_pk_mul_f32 v[130:131], v[130:131], v[188:189]
	v_pk_mul_f32 v[160:161], v[128:129], v[160:161]
	v_pk_mul_f32 v[128:129], v[126:127], v[188:189]
	v_cndmask_b32_e64 v188, 1.0, 0, vcc
	v_cmp_eq_u32_e32 vcc, s34, v183
	s_waitcnt lgkmcnt(7)
	v_pk_mul_f32 v[126:127], v[188:189], v[50:51] op_sel_hi:[0,1]
	s_mov_b32 s0, 0xc0135761
	v_cndmask_b32_e64 v190, 1.0, 0, vcc
	s_waitcnt lgkmcnt(5)
	v_pk_mul_f32 v[194:195], v[190:191], v[54:55] op_sel_hi:[0,1]
	s_waitcnt lgkmcnt(4)
	v_pk_fma_f32 v[192:193], v[194:195], v[192:193], v[58:59]
	v_mov_b64_e32 v[194:195], s[0:1]
	v_pk_fma_f32 v[192:193], v[186:187], v[46:47], v[192:193]
	s_mov_b32 s0, 0x3dd2d3e8
	v_pk_fma_f32 v[126:127], v[126:127], v[198:199], v[192:193]
	v_pk_mul_f32 v[192:193], v[126:127], v[126:127]
	v_pk_fma_f32 v[192:193], v[192:193], s[0:1], v[194:195] op_sel_hi:[1,0,0] neg_lo:[1,0,0] neg_hi:[1,0,0]
	v_pk_mul_f32 v[192:193], v[126:127], v[192:193]
	v_exp_f32_e32 v192, v192
	v_exp_f32_e32 v193, v193
	s_nop 0
	v_pk_add_f32 v[192:193], v[192:193], 1.0 op_sel_hi:[1,0]
	v_rcp_f32_e32 v192, v192
	v_rcp_f32_e32 v193, v193
	s_nop 0
	v_pk_mul_f32 v[126:127], v[126:127], v[192:193]
	v_pk_mul_f32 v[192:193], v[190:191], v[56:57] op_sel_hi:[0,1]
	v_pk_fma_f32 v[156:157], v[192:193], v[156:157], v[60:61]
	v_pk_mul_f32 v[126:127], v[130:131], v[126:127]
	v_pk_mul_f32 v[130:131], v[188:189], v[52:53] op_sel_hi:[0,1]
	v_pk_fma_f32 v[156:157], v[184:185], v[48:49], v[156:157]
	v_cvt_pk_bf16_f32 v126, v126, v127
	v_pk_fma_f32 v[130:131], v[130:131], v[154:155], v[156:157]
	v_pk_mul_f32 v[154:155], v[130:131], v[130:131]
	v_pk_fma_f32 v[154:155], v[154:155], s[0:1], v[194:195] op_sel_hi:[1,0,0] neg_lo:[1,0,0] neg_hi:[1,0,0]
	v_pk_mul_f32 v[154:155], v[130:131], v[154:155]
	v_exp_f32_e32 v154, v154
	v_exp_f32_e32 v155, v155
	s_nop 0
	v_pk_add_f32 v[154:155], v[154:155], 1.0 op_sel_hi:[1,0]
	v_rcp_f32_e32 v154, v154
	v_rcp_f32_e32 v155, v155
	s_nop 0
	v_pk_mul_f32 v[130:131], v[130:131], v[154:155]
	v_pk_mul_f32 v[130:131], v[132:133], v[130:131]
	s_waitcnt lgkmcnt(1)
	v_pk_mul_f32 v[132:133], v[190:191], v[70:71] op_sel_hi:[0,1]
	s_waitcnt lgkmcnt(0)
	v_pk_fma_f32 v[132:133], v[132:133], v[152:153], v[66:67]
	v_cvt_pk_bf16_f32 v127, v130, v131
	v_pk_mul_f32 v[130:131], v[188:189], v[74:75] op_sel_hi:[0,1]
	v_pk_fma_f32 v[132:133], v[148:149], v[62:63], v[132:133]
	v_pk_fma_f32 v[130:131], v[130:131], v[150:151], v[132:133]
	v_pk_mul_f32 v[132:133], v[130:131], v[130:131]
	v_pk_fma_f32 v[132:133], v[132:133], s[0:1], v[194:195] op_sel_hi:[1,0,0] neg_lo:[1,0,0] neg_hi:[1,0,0]
	v_pk_mul_f32 v[132:133], v[130:131], v[132:133]
	v_exp_f32_e32 v132, v132
	v_exp_f32_e32 v133, v133
	s_nop 0
	v_pk_add_f32 v[132:133], v[132:133], 1.0 op_sel_hi:[1,0]
	v_rcp_f32_e32 v132, v132
	v_rcp_f32_e32 v133, v133
	s_nop 0
	v_pk_mul_f32 v[130:131], v[130:131], v[132:133]
	v_pk_mul_f32 v[132:133], v[190:191], v[72:73] op_sel_hi:[0,1]
	v_pk_fma_f32 v[132:133], v[132:133], v[144:145], v[68:69]
	v_pk_mul_f32 v[128:129], v[128:129], v[130:131]
	v_pk_mul_f32 v[130:131], v[188:189], v[76:77] op_sel_hi:[0,1]
	v_pk_fma_f32 v[132:133], v[146:147], v[64:65], v[132:133]
	v_cvt_pk_bf16_f32 v128, v128, v129
	v_pk_fma_f32 v[130:131], v[130:131], v[142:143], v[132:133]
	v_pk_mul_f32 v[132:133], v[130:131], v[130:131]
	v_pk_fma_f32 v[132:133], v[132:133], s[0:1], v[194:195] op_sel_hi:[1,0,0] neg_lo:[1,0,0] neg_hi:[1,0,0]
	v_pk_mul_f32 v[132:133], v[130:131], v[132:133]
	v_exp_f32_e32 v132, v132
	v_exp_f32_e32 v133, v133
	s_nop 0
	v_pk_add_f32 v[132:133], v[132:133], 1.0 op_sel_hi:[1,0]
	v_rcp_f32_e32 v132, v132
	v_rcp_f32_e32 v133, v133
	s_nop 0
	v_pk_mul_f32 v[130:131], v[130:131], v[132:133]
	v_pk_mul_f32 v[130:131], v[160:161], v[130:131]
	v_cvt_pk_bf16_f32 v129, v130, v131
	v_mov_b64_e32 v[130:131], s[18:19]
	v_mad_i64_i32 v[130:131], s[0:1], v181, s27, v[130:131]
	v_lshl_add_u64 v[130:131], v[176:177], 1, v[130:131]
	global_store_dwordx4 v[130:131], v[126:129], off
; #define PG8_LAS __attribute__((address_space(3)))
;     __device__ __forceinline__ void operator()(const f32x4 (&acc_)[2][2][4][2], const Unit& u, int wr, int wc, int fr, int fq) const {
;     ...
;             for (int m = 0; m < 4; ++m) { const float r = xg[1536 + ai * HALF + wr * 64 + m * 16 + fr];
; #pragma unroll
;                 for (int bj = 0; bj < 2; ++bj)
; #pragma unroll
;                     for (int n = 0; n < 2; ++n) acc[ai][bj][m][n] *= r; }
;         typedef float v2f __attribute__((ext_vector_type(2)));
;         const PG8_LAS float* wl = xg + 1024;
; #pragma unroll
;         for (int ai = 0; ai < 2; ++ai) {
;             const int sp = wr == 1 ? ((ai * 2 + 0) * 2 + 1) : (ai == 1 ? ((0 * 2 + 1) * 2 + 1) : -1);
;             const int sn = wr == 0 ? ((ai * 2 + 1) * 2 + 0) : (ai == 0 ? ((1 * 2 + 0) * 2 + 0) : -1);
; #pragma unroll
;             for (int m = 0; m < 4; ++m) {
;                 const int lr = ai * HALF + wr * 64 + m * 16 + fr, t = a_tok0(u.pm) + lr, tq = t & (Tg - 1);
;                 const float mp = tq == 0 ? 0.f : 1.f, mn = tq == Tg - 1 ? 0.f : 1.f;
;                 u32x4 ov;
; #pragma unroll
;                 for (int n = 0; n < 2; ++n) {
;                     const f32x4 w0 = *(const PG8_LAS f32x4*)(wl + jj + 4 * n), w1 = *(const PG8_LAS f32x4*)(wl + 128 + jj + 4 * n), w2 = *(const PG8_LAS f32x4*)(wl + 256 + jj + 4 * n), bb = *(const PG8_LAS f32x4*)(wl + 384 + jj + 4 * n);
;                     f32x4 bp = {0.f, 0.f, 0.f, 0.f}, bn = {0.f, 0.f, 0.f, 0.f};
;                     if (m == 0 && sp >= 0) bp = *(const PG8_LAS f32x4*)(xg + sp * 128 + jj + 4 * n) * xg[1536 + ai * HALF + wr * 64 - 1];
;                     if (m == 3 && sn >= 0) bn = *(const PG8_LAS f32x4*)(xg + sn * 128 + jj + 4 * n) * xg[1536 + ai * HALF + wr * 64 + 64];
; #pragma unroll
;                     for (int eh = 0; eh < 2; ++eh) { v2f gv, p, q, up;
; #pragma unroll
;                         for (int k = 0; k < 2; ++k) { const int e = 2 * eh + k; const float g0 = acc[ai][0][m][n][e];
;                             const float pa = m > 0 ? dpp_ror1(acc[ai][0][m > 0 ? m - 1 : 0][n][e]) : bp[e];
;                             const float qa = m < 3 ? dpp_ror15(acc[ai][0][m < 3 ? m + 1 : 3][n][e]) : bn[e];
;                             gv[k] = g0; up[k] = acc[ai][1][m][n][e];
.LBB0_665:
	s_or_b64 exec, exec, s[46:47]
	v_pk_mul_f32 v[124:125], v[124:125], v[178:179] op_sel_hi:[1,0]
	v_pk_mul_f32 v[122:123], v[122:123], v[178:179] op_sel_hi:[1,0]
	v_pk_mul_f32 v[120:121], v[120:121], v[178:179] op_sel_hi:[1,0]
	v_pk_mul_f32 v[118:119], v[118:119], v[178:179] op_sel_hi:[1,0]
	v_add_u32_e32 v154, s33, v222
	v_mov_b32_dpp v150, v186 row_ror:1 row_mask:0xf bank_mask:0xf
	v_mov_b32_dpp v152, v122 row_ror:15 row_mask:0xf bank_mask:0xf
	v_mov_b32_dpp v151, v187 row_ror:1 row_mask:0xf bank_mask:0xf
	v_mov_b32_dpp v153, v123 row_ror:15 row_mask:0xf bank_mask:0xf
	v_mov_b32_dpp v142, v184 row_ror:1 row_mask:0xf bank_mask:0xf
	v_mov_b32_dpp v144, v124 row_ror:15 row_mask:0xf bank_mask:0xf
	v_mov_b32_dpp v143, v185 row_ror:1 row_mask:0xf bank_mask:0xf
	v_mov_b32_dpp v145, v125 row_ror:15 row_mask:0xf bank_mask:0xf
	v_mov_b32_dpp v130, v148 row_ror:1 row_mask:0xf bank_mask:0xf
	v_mov_b32_dpp v132, v118 row_ror:15 row_mask:0xf bank_mask:0xf
	v_mov_b32_dpp v131, v149 row_ror:1 row_mask:0xf bank_mask:0xf
	v_mov_b32_dpp v133, v119 row_ror:15 row_mask:0xf bank_mask:0xf
	v_mov_b32_dpp v126, v146 row_ror:1 row_mask:0xf bank_mask:0xf
	v_mov_b32_dpp v128, v120 row_ror:15 row_mask:0xf bank_mask:0xf
	v_mov_b32_dpp v127, v147 row_ror:1 row_mask:0xf bank_mask:0xf
	v_mov_b32_dpp v129, v121 row_ror:15 row_mask:0xf bank_mask:0xf
	v_cmp_gt_i32_e32 vcc, s26, v154
	v_mov_b32_dpp v150, v138 row_shr:1 row_mask:0xf bank_mask:0xf
	v_mov_b32_dpp v152, v138 row_shl:1 row_mask:0xf bank_mask:0xf
	v_mov_b32_dpp v151, v139 row_shr:1 row_mask:0xf bank_mask:0xf
	v_mov_b32_dpp v153, v139 row_shl:1 row_mask:0xf bank_mask:0xf
	v_mov_b32_dpp v142, v140 row_shr:1 row_mask:0xf bank_mask:0xf
	v_mov_b32_dpp v144, v140 row_shl:1 row_mask:0xf bank_mask:0xf
	v_mov_b32_dpp v143, v141 row_shr:1 row_mask:0xf bank_mask:0xf
	v_mov_b32_dpp v145, v141 row_shl:1 row_mask:0xf bank_mask:0xf
	v_mov_b32_dpp v130, v134 row_shr:1 row_mask:0xf bank_mask:0xf
	v_mov_b32_dpp v132, v134 row_shl:1 row_mask:0xf bank_mask:0xf
	v_mov_b32_dpp v131, v135 row_shr:1 row_mask:0xf bank_mask:0xf
	v_mov_b32_dpp v133, v135 row_shl:1 row_mask:0xf bank_mask:0xf
	v_mov_b32_dpp v126, v136 row_shr:1 row_mask:0xf bank_mask:0xf
	v_mov_b32_dpp v128, v136 row_shl:1 row_mask:0xf bank_mask:0xf
	v_mov_b32_dpp v127, v137 row_shr:1 row_mask:0xf bank_mask:0xf
	v_mov_b32_dpp v129, v137 row_shl:1 row_mask:0xf bank_mask:0xf
	s_and_b64 s[0:1], s[10:11], vcc
	s_and_saveexec_b64 s[46:47], s[0:1]
	s_cbranch_execz .LBB0_667
	v_and_b32_e32 v149, s34, v154
	v_cmp_eq_u32_e32 vcc, 0, v149
	v_mov_b32_e32 v183, v182
	v_mov_b32_e32 v146, v182
	v_cndmask_b32_e64 v148, 1.0, 0, vcc
	v_cmp_eq_u32_e32 vcc, s34, v149
	v_mov_b32_e32 v147, v182
	v_pk_mul_f32 v[116:117], v[116:117], v[146:147]
	v_cndmask_b32_e64 v156, 1.0, 0, vcc
	s_waitcnt lgkmcnt(5)
	v_pk_mul_f32 v[160:161], v[156:157], v[54:55] op_sel_hi:[0,1]
	s_waitcnt lgkmcnt(4)
	v_pk_fma_f32 v[152:153], v[160:161], v[152:153], v[58:59]
	v_pk_mul_f32 v[146:147], v[112:113], v[146:147]
	v_pk_mul_f32 v[112:113], v[110:111], v[182:183]
	v_pk_mul_f32 v[110:111], v[148:149], v[50:51] op_sel_hi:[0,1]
	v_pk_fma_f32 v[152:153], v[138:139], v[46:47], v[152:153]
	s_mov_b32 s0, 0xc0135761
	v_pk_fma_f32 v[110:111], v[110:111], v[150:151], v[152:153]
	v_mov_b64_e32 v[152:153], s[0:1]
	v_pk_mul_f32 v[150:151], v[110:111], v[110:111]
	s_mov_b32 s0, 0x3dd2d3e8
	v_pk_fma_f32 v[150:151], v[150:151], s[0:1], v[152:153] op_sel_hi:[1,0,0] neg_lo:[1,0,0] neg_hi:[1,0,0]
	v_pk_mul_f32 v[114:115], v[114:115], v[182:183]
	v_pk_mul_f32 v[150:151], v[110:111], v[150:151]
	v_exp_f32_e32 v150, v150
	v_exp_f32_e32 v151, v151
	s_nop 0
	v_pk_add_f32 v[150:151], v[150:151], 1.0 op_sel_hi:[1,0]
	v_rcp_f32_e32 v150, v150
	v_rcp_f32_e32 v151, v151
	s_nop 0
	v_pk_mul_f32 v[110:111], v[110:111], v[150:151]
	v_pk_mul_f32 v[150:151], v[156:157], v[56:57] op_sel_hi:[0,1]
	v_pk_fma_f32 v[144:145], v[150:151], v[144:145], v[60:61]
	v_pk_mul_f32 v[110:111], v[114:115], v[110:111]
	v_pk_mul_f32 v[114:115], v[148:149], v[52:53] op_sel_hi:[0,1]
	v_pk_fma_f32 v[144:145], v[140:141], v[48:49], v[144:145]
	v_cvt_pk_bf16_f32 v110, v110, v111
	v_pk_fma_f32 v[114:115], v[114:115], v[142:143], v[144:145]
	v_pk_mul_f32 v[142:143], v[114:115], v[114:115]
	v_pk_fma_f32 v[142:143], v[142:143], s[0:1], v[152:153] op_sel_hi:[1,0,0] neg_lo:[1,0,0] neg_hi:[1,0,0]
	v_pk_mul_f32 v[142:143], v[114:115], v[142:143]
	v_exp_f32_e32 v142, v142
	v_exp_f32_e32 v143, v143
	s_nop 0
	v_pk_add_f32 v[142:143], v[142:143], 1.0 op_sel_hi:[1,0]
	v_rcp_f32_e32 v142, v142
	v_rcp_f32_e32 v143, v143
	s_nop 0
	v_pk_mul_f32 v[114:115], v[114:115], v[142:143]
	v_pk_mul_f32 v[114:115], v[116:117], v[114:115]
	s_waitcnt lgkmcnt(1)
	v_pk_mul_f32 v[116:117], v[156:157], v[70:71] op_sel_hi:[0,1]
	s_waitcnt lgkmcnt(0)
	v_pk_fma_f32 v[116:117], v[116:117], v[132:133], v[66:67]
	v_cvt_pk_bf16_f32 v111, v114, v115
	v_pk_mul_f32 v[114:115], v[148:149], v[74:75] op_sel_hi:[0,1]
	v_pk_fma_f32 v[116:117], v[134:135], v[62:63], v[116:117]
	v_pk_fma_f32 v[114:115], v[114:115], v[130:131], v[116:117]
	v_pk_mul_f32 v[116:117], v[114:115], v[114:115]
	v_pk_fma_f32 v[116:117], v[116:117], s[0:1], v[152:153] op_sel_hi:[1,0,0] neg_lo:[1,0,0] neg_hi:[1,0,0]
	v_pk_mul_f32 v[116:117], v[114:115], v[116:117]
	v_exp_f32_e32 v116, v116
	v_exp_f32_e32 v117, v117
	s_nop 0
	v_pk_add_f32 v[116:117], v[116:117], 1.0 op_sel_hi:[1,0]
	v_rcp_f32_e32 v116, v116
	v_rcp_f32_e32 v117, v117
	s_nop 0
	v_pk_mul_f32 v[114:115], v[114:115], v[116:117]
	v_pk_mul_f32 v[116:117], v[156:157], v[72:73] op_sel_hi:[0,1]
	v_pk_fma_f32 v[116:117], v[116:117], v[128:129], v[68:69]
	v_pk_mul_f32 v[112:113], v[112:113], v[114:115]
	v_pk_mul_f32 v[114:115], v[148:149], v[76:77] op_sel_hi:[0,1]
	v_pk_fma_f32 v[116:117], v[136:137], v[64:65], v[116:117]
	v_cvt_pk_bf16_f32 v112, v112, v113
	v_pk_fma_f32 v[114:115], v[114:115], v[126:127], v[116:117]
	v_pk_mul_f32 v[116:117], v[114:115], v[114:115]
	v_pk_fma_f32 v[116:117], v[116:117], s[0:1], v[152:153] op_sel_hi:[1,0,0] neg_lo:[1,0,0] neg_hi:[1,0,0]
	v_pk_mul_f32 v[116:117], v[114:115], v[116:117]
	v_exp_f32_e32 v116, v116
	v_exp_f32_e32 v117, v117
	s_nop 0
	v_pk_add_f32 v[116:117], v[116:117], 1.0 op_sel_hi:[1,0]
	v_rcp_f32_e32 v116, v116
	v_rcp_f32_e32 v117, v117
	s_nop 0
	v_pk_mul_f32 v[114:115], v[114:115], v[116:117]
	v_pk_mul_f32 v[114:115], v[146:147], v[114:115]
	v_cvt_pk_bf16_f32 v113, v114, v115
	v_mov_b64_e32 v[114:115], s[18:19]
	v_mad_i64_i32 v[114:115], s[0:1], v154, s27, v[114:115]
	v_lshl_add_u64 v[114:115], v[176:177], 1, v[114:115]
	global_store_dwordx4 v[114:115], v[110:113], off
; #define PG8_LAS __attribute__((address_space(3)))
;     __device__ __forceinline__ void operator()(const f32x4 (&acc_)[2][2][4][2], const Unit& u, int wr, int wc, int fr, int fq) const {
;     ...
;             for (int m = 0; m < 4; ++m) { const float r = xg[1536 + ai * HALF + wr * 64 + m * 16 + fr];
; #pragma unroll
;                 for (int bj = 0; bj < 2; ++bj)
; #pragma unroll
;                     for (int n = 0; n < 2; ++n) acc[ai][bj][m][n] *= r; }
;         typedef float v2f __attribute__((ext_vector_type(2)));
;         const PG8_LAS float* wl = xg + 1024;
; #pragma unroll
;         for (int ai = 0; ai < 2; ++ai) {
;             const int sp = wr == 1 ? ((ai * 2 + 0) * 2 + 1) : (ai == 1 ? ((0 * 2 + 1) * 2 + 1) : -1);
;             const int sn = wr == 0 ? ((ai * 2 + 1) * 2 + 0) : (ai == 0 ? ((1 * 2 + 0) * 2 + 0) : -1);
; #pragma unroll
;             for (int m = 0; m < 4; ++m) {
;                 const int lr = ai * HALF + wr * 64 + m * 16 + fr, t = a_tok0(u.pm) + lr, tq = t & (Tg - 1);
;                 const float mp = tq == 0 ? 0.f : 1.f, mn = tq == Tg - 1 ? 0.f : 1.f;
;                 u32x4 ov;
; #pragma unroll
;                 for (int n = 0; n < 2; ++n) {
;                     const f32x4 w0 = *(const PG8_LAS f32x4*)(wl + jj + 4 * n), w1 = *(const PG8_LAS f32x4*)(wl + 128 + jj + 4 * n), w2 = *(const PG8_LAS f32x4*)(wl + 256 + jj + 4 * n), bb = *(const PG8_LAS f32x4*)(wl + 384 + jj + 4 * n);
;                     f32x4 bp = {0.f, 0.f, 0.f, 0.f}, bn = {0.f, 0.f, 0.f, 0.f};
;                     if (m == 0 && sp >= 0) bp = *(const PG8_LAS f32x4*)(xg + sp * 128 + jj + 4 * n) * xg[1536 + ai * HALF + wr * 64 - 1];
;                     if (m == 3 && sn >= 0) bn = *(const PG8_LAS f32x4*)(xg + sn * 128 + jj + 4 * n) * xg[1536 + ai * HALF + wr * 64 + 64];
; #pragma unroll
;                     for (int eh = 0; eh < 2; ++eh) { v2f gv, p, q, up;
; #pragma unroll
;                         for (int k = 0; k < 2; ++k) { const int e = 2 * eh + k; const float g0 = acc[ai][0][m][n][e];
;                             const float pa = m > 0 ? dpp_ror1(acc[ai][0][m > 0 ? m - 1 : 0][n][e]) : bp[e];
;                             const float qa = m < 3 ? dpp_ror15(acc[ai][0][m < 3 ? m + 1 : 3][n][e]) : bn[e];
;                             gv[k] = g0; up[k] = acc[ai][1][m][n][e];
.LBB0_667:
	s_or_b64 exec, exec, s[46:47]
	v_mov_b32_e32 v114, s79
	ds_read_b128 v[110:113], v240
	ds_read_b32 v144, v114 offset:6400
	ds_read_b128 v[114:117], v240 offset:16
	v_add_u32_e32 v142, s33, v223
	s_waitcnt lgkmcnt(1)
	v_pk_mul_f32 v[126:127], v[112:113], v[144:145] op_sel_hi:[1,0]
	v_pk_mul_f32 v[132:133], v[110:111], v[144:145] op_sel_hi:[1,0]
	s_waitcnt lgkmcnt(0)
	v_pk_mul_f32 v[110:111], v[144:145], v[116:117] op_sel_hi:[0,1]
	v_pk_mul_f32 v[116:117], v[144:145], v[114:115] op_sel_hi:[0,1]
	v_mov_b32_dpp v130, v138 row_ror:1 row_mask:0xf bank_mask:0xf
	v_mov_b32_dpp v131, v139 row_ror:1 row_mask:0xf bank_mask:0xf
	v_mov_b32_dpp v128, v140 row_ror:1 row_mask:0xf bank_mask:0xf
	v_mov_b32_dpp v129, v141 row_ror:1 row_mask:0xf bank_mask:0xf
	v_mov_b32_dpp v114, v134 row_ror:1 row_mask:0xf bank_mask:0xf
	v_mov_b32_dpp v115, v135 row_ror:1 row_mask:0xf bank_mask:0xf
	v_mov_b32_dpp v112, v136 row_ror:1 row_mask:0xf bank_mask:0xf
	v_mov_b32_dpp v113, v137 row_ror:1 row_mask:0xf bank_mask:0xf
	v_cmp_gt_i32_e32 vcc, s26, v142
	v_mov_b32_dpp v130, v122 row_shr:1 row_mask:0xf bank_mask:0xf
	v_mov_b32_dpp v132, v122 row_shl:1 row_mask:0xf bank_mask:0xf
	v_mov_b32_dpp v131, v123 row_shr:1 row_mask:0xf bank_mask:0xf
	v_mov_b32_dpp v133, v123 row_shl:1 row_mask:0xf bank_mask:0xf
	v_mov_b32_dpp v128, v124 row_shr:1 row_mask:0xf bank_mask:0xf
	v_mov_b32_dpp v126, v124 row_shl:1 row_mask:0xf bank_mask:0xf
	v_mov_b32_dpp v129, v125 row_shr:1 row_mask:0xf bank_mask:0xf
	v_mov_b32_dpp v127, v125 row_shl:1 row_mask:0xf bank_mask:0xf
	v_mov_b32_dpp v114, v118 row_shr:1 row_mask:0xf bank_mask:0xf
	v_mov_b32_dpp v116, v118 row_shl:1 row_mask:0xf bank_mask:0xf
	v_mov_b32_dpp v115, v119 row_shr:1 row_mask:0xf bank_mask:0xf
	v_mov_b32_dpp v117, v119 row_shl:1 row_mask:0xf bank_mask:0xf
	v_mov_b32_dpp v112, v120 row_shr:1 row_mask:0xf bank_mask:0xf
	v_mov_b32_dpp v110, v120 row_shl:1 row_mask:0xf bank_mask:0xf
	v_mov_b32_dpp v113, v121 row_shr:1 row_mask:0xf bank_mask:0xf
	v_mov_b32_dpp v111, v121 row_shl:1 row_mask:0xf bank_mask:0xf
	s_and_b64 s[0:1], s[12:13], vcc
	s_and_saveexec_b64 s[46:47], s[0:1]
	s_cbranch_execz .LBB0_669
	v_mov_b32_e32 v134, v178
	v_mov_b32_e32 v135, v178
	v_mov_b32_e32 v136, v178
	v_mov_b32_e32 v137, v178
	v_pk_mul_f32 v[108:109], v[108:109], v[136:137]
	v_pk_mul_f32 v[106:107], v[106:107], v[134:135]
	v_pk_mul_f32 v[136:137], v[104:105], v[136:137]
	v_pk_mul_f32 v[104:105], v[102:103], v[134:135]
	v_and_b32_e32 v135, s34, v142
	v_cmp_eq_u32_e32 vcc, 0, v135
	s_mov_b32 s0, 0xc0135761
	s_nop 0
	v_cndmask_b32_e64 v134, 1.0, 0, vcc
	v_cmp_eq_u32_e32 vcc, s34, v135
	v_pk_mul_f32 v[102:103], v[134:135], v[50:51] op_sel_hi:[0,1]
	s_nop 0
	v_cndmask_b32_e64 v138, 1.0, 0, vcc
	v_pk_mul_f32 v[140:141], v[138:139], v[54:55] op_sel_hi:[0,1]
	v_pk_fma_f32 v[132:133], v[140:141], v[132:133], v[58:59]
	v_pk_mul_f32 v[140:141], v[138:139], v[56:57] op_sel_hi:[0,1]
	v_pk_fma_f32 v[122:123], v[122:123], v[46:47], v[132:133]
	v_pk_fma_f32 v[126:127], v[140:141], v[126:127], v[60:61]
	v_pk_fma_f32 v[102:103], v[102:103], v[130:131], v[122:123]
	v_pk_mul_f32 v[132:133], v[134:135], v[52:53] op_sel_hi:[0,1]
	v_pk_fma_f32 v[124:125], v[124:125], v[48:49], v[126:127]
	v_pk_mul_f32 v[122:123], v[102:103], v[102:103]
	v_mov_b64_e32 v[130:131], s[0:1]
	s_mov_b32 s0, 0x3dd2d3e8
	v_pk_fma_f32 v[124:125], v[132:133], v[128:129], v[124:125]
	v_pk_fma_f32 v[122:123], v[122:123], s[0:1], v[130:131] op_sel_hi:[1,0,0] neg_lo:[1,0,0] neg_hi:[1,0,0]
	v_pk_mul_f32 v[126:127], v[124:125], v[124:125]
	v_pk_mul_f32 v[122:123], v[102:103], v[122:123]
	v_pk_fma_f32 v[126:127], v[126:127], s[0:1], v[130:131] op_sel_hi:[1,0,0] neg_lo:[1,0,0] neg_hi:[1,0,0]
	v_exp_f32_e32 v122, v122
	v_exp_f32_e32 v123, v123
	v_pk_mul_f32 v[126:127], v[124:125], v[126:127]
	v_pk_add_f32 v[122:123], v[122:123], 1.0 op_sel_hi:[1,0]
	v_exp_f32_e32 v126, v126
	v_exp_f32_e32 v127, v127
	v_rcp_f32_e32 v122, v122
	v_rcp_f32_e32 v123, v123
	v_pk_add_f32 v[126:127], v[126:127], 1.0 op_sel_hi:[1,0]
	v_rcp_f32_e32 v126, v126
	v_rcp_f32_e32 v127, v127
	v_pk_mul_f32 v[102:103], v[102:103], v[122:123]
	v_pk_mul_f32 v[102:103], v[106:107], v[102:103]
	v_pk_mul_f32 v[106:107], v[124:125], v[126:127]
	v_cvt_pk_bf16_f32 v102, v102, v103
	v_pk_mul_f32 v[106:107], v[108:109], v[106:107]
	v_pk_mul_f32 v[108:109], v[138:139], v[70:71] op_sel_hi:[0,1]
	v_pk_fma_f32 v[108:109], v[108:109], v[116:117], v[66:67]
	v_pk_mul_f32 v[116:117], v[138:139], v[72:73] op_sel_hi:[0,1]
	v_cvt_pk_bf16_f32 v103, v106, v107
	v_pk_mul_f32 v[106:107], v[134:135], v[74:75] op_sel_hi:[0,1]
	v_pk_fma_f32 v[108:109], v[118:119], v[62:63], v[108:109]
	v_pk_fma_f32 v[110:111], v[116:117], v[110:111], v[68:69]
	v_pk_fma_f32 v[106:107], v[106:107], v[114:115], v[108:109]
	v_pk_mul_f32 v[114:115], v[134:135], v[76:77] op_sel_hi:[0,1]
	v_pk_fma_f32 v[110:111], v[120:121], v[64:65], v[110:111]
	v_pk_mul_f32 v[108:109], v[106:107], v[106:107]
	v_pk_fma_f32 v[110:111], v[114:115], v[112:113], v[110:111]
	v_pk_fma_f32 v[108:109], v[108:109], s[0:1], v[130:131] op_sel_hi:[1,0,0] neg_lo:[1,0,0] neg_hi:[1,0,0]
	v_pk_mul_f32 v[112:113], v[110:111], v[110:111]
	v_pk_mul_f32 v[108:109], v[106:107], v[108:109]
	v_pk_fma_f32 v[112:113], v[112:113], s[0:1], v[130:131] op_sel_hi:[1,0,0] neg_lo:[1,0,0] neg_hi:[1,0,0]
	v_exp_f32_e32 v108, v108
	v_exp_f32_e32 v109, v109
	v_pk_mul_f32 v[112:113], v[110:111], v[112:113]
	v_pk_add_f32 v[108:109], v[108:109], 1.0 op_sel_hi:[1,0]
	v_exp_f32_e32 v112, v112
	v_exp_f32_e32 v113, v113
	v_rcp_f32_e32 v108, v108
	v_rcp_f32_e32 v109, v109
	v_pk_add_f32 v[112:113], v[112:113], 1.0 op_sel_hi:[1,0]
	v_rcp_f32_e32 v112, v112
	v_rcp_f32_e32 v113, v113
	v_pk_mul_f32 v[106:107], v[106:107], v[108:109]
	v_pk_mul_f32 v[104:105], v[104:105], v[106:107]
	v_pk_mul_f32 v[106:107], v[110:111], v[112:113]
	v_cvt_pk_bf16_f32 v104, v104, v105
	v_pk_mul_f32 v[106:107], v[136:137], v[106:107]
	v_cvt_pk_bf16_f32 v105, v106, v107
	v_mov_b64_e32 v[106:107], s[18:19]
	v_mad_i64_i32 v[106:107], s[0:1], v142, s27, v[106:107]
	v_lshl_add_u64 v[106:107], v[176:177], 1, v[106:107]
	global_store_dwordx4 v[106:107], v[102:105], off
; #define PG8_LAS __attribute__((address_space(3)))
;     __device__ __forceinline__ void operator()(const f32x4 (&acc_)[2][2][4][2], const Unit& u, int wr, int wc, int fr, int fq) const {
;     ...
;             for (int m = 0; m < 4; ++m) { const float r = xg[1536 + ai * HALF + wr * 64 + m * 16 + fr];
; #pragma unroll
;                 for (int bj = 0; bj < 2; ++bj)
; #pragma unroll
;                     for (int n = 0; n < 2; ++n) acc[ai][bj][m][n] *= r; }
;         typedef float v2f __attribute__((ext_vector_type(2)));
;         const PG8_LAS float* wl = xg + 1024;
; #pragma unroll
;         for (int ai = 0; ai < 2; ++ai) {
;             const int sp = wr == 1 ? ((ai * 2 + 0) * 2 + 1) : (ai == 1 ? ((0 * 2 + 1) * 2 + 1) : -1);
;             const int sn = wr == 0 ? ((ai * 2 + 1) * 2 + 0) : (ai == 0 ? ((1 * 2 + 0) * 2 + 0) : -1);
; #pragma unroll
;             for (int m = 0; m < 4; ++m) {
;                 const int lr = ai * HALF + wr * 64 + m * 16 + fr, t = a_tok0(u.pm) + lr, tq = t & (Tg - 1);
;                 const float mp = tq == 0 ? 0.f : 1.f, mn = tq == Tg - 1 ? 0.f : 1.f;
;                 u32x4 ov;
; #pragma unroll
;                 for (int n = 0; n < 2; ++n) {
;                     const f32x4 w0 = *(const PG8_LAS f32x4*)(wl + jj + 4 * n), w1 = *(const PG8_LAS f32x4*)(wl + 128 + jj + 4 * n), w2 = *(const PG8_LAS f32x4*)(wl + 256 + jj + 4 * n), bb = *(const PG8_LAS f32x4*)(wl + 384 + jj + 4 * n);
;                     f32x4 bp = {0.f, 0.f, 0.f, 0.f}, bn = {0.f, 0.f, 0.f, 0.f};
;                     if (m == 0 && sp >= 0) bp = *(const PG8_LAS f32x4*)(xg + sp * 128 + jj + 4 * n) * xg[1536 + ai * HALF + wr * 64 - 1];
;                     if (m == 3 && sn >= 0) bn = *(const PG8_LAS f32x4*)(xg + sn * 128 + jj + 4 * n) * xg[1536 + ai * HALF + wr * 64 + 64];
; #pragma unroll
;                     for (int eh = 0; eh < 2; ++eh) { v2f gv, p, q, up;
; #pragma unroll
;                         for (int k = 0; k < 2; ++k) { const int e = 2 * eh + k; const float g0 = acc[ai][0][m][n][e];
;                             const float pa = m > 0 ? dpp_ror1(acc[ai][0][m > 0 ? m - 1 : 0][n][e]) : bp[e];
;                             const float qa = m < 3 ? dpp_ror15(acc[ai][0][m < 3 ? m + 1 : 3][n][e]) : bn[e];
;                             gv[k] = g0; up[k] = acc[ai][1][m][n][e];
.LBB0_669:
	s_or_b64 exec, exec, s[46:47]
	s_nop 0
	v_pk_mul_f32 v[102:103], v[88:89], v[180:181] op_sel_hi:[1,0]
	v_pk_mul_f32 v[104:105], v[86:87], v[180:181] op_sel_hi:[1,0]
	v_mov_b32_e32 v88, v179
	v_mov_b32_e32 v86, s79
	v_pk_mul_f32 v[106:107], v[92:93], v[180:181] op_sel_hi:[1,0]
	v_pk_mul_f32 v[108:109], v[90:91], v[180:181] op_sel_hi:[1,0]
	v_pk_mul_f32 v[90:91], v[100:101], v[88:89] op_sel_hi:[1,0]
	v_pk_mul_f32 v[92:93], v[98:99], v[88:89] op_sel_hi:[1,0]
	ds_read_b128 v[98:101], v241
	ds_read_b32 v124, v86 offset:6652
	ds_read_b128 v[120:123], v241 offset:16
	v_pk_mul_f32 v[86:87], v[96:97], v[88:89] op_sel_hi:[1,0]
	v_pk_mul_f32 v[88:89], v[94:95], v[88:89] op_sel_hi:[1,0]
	v_add_u32_e32 v118, s33, v224
	s_waitcnt lgkmcnt(1)
	v_pk_mul_f32 v[110:111], v[100:101], v[124:125] op_sel_hi:[1,0]
	v_pk_mul_f32 v[114:115], v[98:99], v[124:125] op_sel_hi:[1,0]
	v_mov_b32_dpp v116, v92 row_ror:15 row_mask:0xf bank_mask:0xf
	v_mov_b32_dpp v117, v93 row_ror:15 row_mask:0xf bank_mask:0xf
	v_mov_b32_dpp v112, v90 row_ror:15 row_mask:0xf bank_mask:0xf
	v_mov_b32_dpp v113, v91 row_ror:15 row_mask:0xf bank_mask:0xf
	s_waitcnt lgkmcnt(0)
	v_pk_mul_f32 v[94:95], v[124:125], v[122:123] op_sel_hi:[0,1]
	v_pk_mul_f32 v[98:99], v[124:125], v[120:121] op_sel_hi:[0,1]
	v_mov_b32_dpp v100, v88 row_ror:15 row_mask:0xf bank_mask:0xf
	v_mov_b32_dpp v101, v89 row_ror:15 row_mask:0xf bank_mask:0xf
	v_mov_b32_dpp v96, v86 row_ror:15 row_mask:0xf bank_mask:0xf
	v_mov_b32_dpp v97, v87 row_ror:15 row_mask:0xf bank_mask:0xf
	v_cmp_gt_i32_e32 vcc, s26, v118
	v_mov_b32_dpp v114, v108 row_shr:1 row_mask:0xf bank_mask:0xf
	v_mov_b32_dpp v116, v108 row_shl:1 row_mask:0xf bank_mask:0xf
	v_mov_b32_dpp v115, v109 row_shr:1 row_mask:0xf bank_mask:0xf
	v_mov_b32_dpp v117, v109 row_shl:1 row_mask:0xf bank_mask:0xf
	v_mov_b32_dpp v110, v106 row_shr:1 row_mask:0xf bank_mask:0xf
	v_mov_b32_dpp v112, v106 row_shl:1 row_mask:0xf bank_mask:0xf
	v_mov_b32_dpp v111, v107 row_shr:1 row_mask:0xf bank_mask:0xf
	v_mov_b32_dpp v113, v107 row_shl:1 row_mask:0xf bank_mask:0xf
	v_mov_b32_dpp v98, v104 row_shr:1 row_mask:0xf bank_mask:0xf
	v_mov_b32_dpp v100, v104 row_shl:1 row_mask:0xf bank_mask:0xf
	v_mov_b32_dpp v99, v105 row_shr:1 row_mask:0xf bank_mask:0xf
	v_mov_b32_dpp v101, v105 row_shl:1 row_mask:0xf bank_mask:0xf
	v_mov_b32_dpp v94, v102 row_shr:1 row_mask:0xf bank_mask:0xf
	v_mov_b32_dpp v96, v102 row_shl:1 row_mask:0xf bank_mask:0xf
	v_mov_b32_dpp v95, v103 row_shr:1 row_mask:0xf bank_mask:0xf
	v_mov_b32_dpp v97, v103 row_shl:1 row_mask:0xf bank_mask:0xf
	s_and_b64 s[0:1], s[14:15], vcc
	s_and_saveexec_b64 s[46:47], s[0:1]
	s_cbranch_execz .LBB0_671
	v_and_b32_e32 v119, s34, v118
	v_cmp_eq_u32_e32 vcc, 0, v119
	v_mov_b32_e32 v181, v180
	v_mov_b32_e32 v120, v180
	v_cndmask_b32_e64 v122, 1.0, 0, vcc
	v_cmp_eq_u32_e32 vcc, s34, v119
	v_mov_b32_e32 v121, v180
	v_pk_mul_f32 v[84:85], v[84:85], v[120:121]
	v_cndmask_b32_e64 v124, 1.0, 0, vcc
	v_pk_mul_f32 v[126:127], v[124:125], v[54:55] op_sel_hi:[0,1]
	v_pk_fma_f32 v[116:117], v[126:127], v[116:117], v[58:59]
	v_pk_mul_f32 v[120:121], v[80:81], v[120:121]
	v_pk_mul_f32 v[80:81], v[78:79], v[180:181]
	v_pk_mul_f32 v[78:79], v[122:123], v[50:51] op_sel_hi:[0,1]
	v_pk_fma_f32 v[116:117], v[108:109], v[46:47], v[116:117]
	s_mov_b32 s0, 0xc0135761
	v_pk_fma_f32 v[78:79], v[78:79], v[114:115], v[116:117]
	v_mov_b64_e32 v[116:117], s[0:1]
	v_pk_mul_f32 v[114:115], v[78:79], v[78:79]
	s_mov_b32 s0, 0x3dd2d3e8
	v_pk_fma_f32 v[114:115], v[114:115], s[0:1], v[116:117] op_sel_hi:[1,0,0] neg_lo:[1,0,0] neg_hi:[1,0,0]
	v_pk_mul_f32 v[82:83], v[82:83], v[180:181]
	v_pk_mul_f32 v[114:115], v[78:79], v[114:115]
	v_exp_f32_e32 v114, v114
	v_exp_f32_e32 v115, v115
	s_nop 0
	v_pk_add_f32 v[114:115], v[114:115], 1.0 op_sel_hi:[1,0]
	v_rcp_f32_e32 v114, v114
	v_rcp_f32_e32 v115, v115
	s_nop 0
	v_pk_mul_f32 v[78:79], v[78:79], v[114:115]
	v_pk_mul_f32 v[114:115], v[124:125], v[56:57] op_sel_hi:[0,1]
	v_pk_fma_f32 v[112:113], v[114:115], v[112:113], v[60:61]
	v_pk_mul_f32 v[78:79], v[82:83], v[78:79]
	v_pk_mul_f32 v[82:83], v[122:123], v[52:53] op_sel_hi:[0,1]
	v_pk_fma_f32 v[112:113], v[106:107], v[48:49], v[112:113]
	v_cvt_pk_bf16_f32 v78, v78, v79
	v_pk_fma_f32 v[82:83], v[82:83], v[110:111], v[112:113]
	v_pk_mul_f32 v[110:111], v[82:83], v[82:83]
	v_pk_fma_f32 v[110:111], v[110:111], s[0:1], v[116:117] op_sel_hi:[1,0,0] neg_lo:[1,0,0] neg_hi:[1,0,0]
	v_pk_mul_f32 v[110:111], v[82:83], v[110:111]
	v_exp_f32_e32 v110, v110
	v_exp_f32_e32 v111, v111
	s_nop 0
	v_pk_add_f32 v[110:111], v[110:111], 1.0 op_sel_hi:[1,0]
	v_rcp_f32_e32 v110, v110
	v_rcp_f32_e32 v111, v111
	s_nop 0
	v_pk_mul_f32 v[82:83], v[82:83], v[110:111]
	v_pk_mul_f32 v[82:83], v[84:85], v[82:83]
	v_pk_mul_f32 v[84:85], v[124:125], v[70:71] op_sel_hi:[0,1]
	v_pk_fma_f32 v[84:85], v[84:85], v[100:101], v[66:67]
	v_cvt_pk_bf16_f32 v79, v82, v83
	v_pk_mul_f32 v[82:83], v[122:123], v[74:75] op_sel_hi:[0,1]
	v_pk_fma_f32 v[84:85], v[104:105], v[62:63], v[84:85]
	v_pk_fma_f32 v[82:83], v[82:83], v[98:99], v[84:85]
	v_pk_mul_f32 v[84:85], v[82:83], v[82:83]
	v_pk_fma_f32 v[84:85], v[84:85], s[0:1], v[116:117] op_sel_hi:[1,0,0] neg_lo:[1,0,0] neg_hi:[1,0,0]
	v_pk_mul_f32 v[84:85], v[82:83], v[84:85]
	v_exp_f32_e32 v84, v84
	v_exp_f32_e32 v85, v85
	s_nop 0
	v_pk_add_f32 v[84:85], v[84:85], 1.0 op_sel_hi:[1,0]
	v_rcp_f32_e32 v84, v84
	v_rcp_f32_e32 v85, v85
	s_nop 0
	v_pk_mul_f32 v[82:83], v[82:83], v[84:85]
	v_pk_mul_f32 v[84:85], v[124:125], v[72:73] op_sel_hi:[0,1]
	v_pk_fma_f32 v[84:85], v[84:85], v[96:97], v[68:69]
	v_pk_mul_f32 v[80:81], v[80:81], v[82:83]
	v_pk_mul_f32 v[82:83], v[122:123], v[76:77] op_sel_hi:[0,1]
	v_pk_fma_f32 v[84:85], v[102:103], v[64:65], v[84:85]
	v_cvt_pk_bf16_f32 v80, v80, v81
	v_pk_fma_f32 v[82:83], v[82:83], v[94:95], v[84:85]
	v_pk_mul_f32 v[84:85], v[82:83], v[82:83]
	v_pk_fma_f32 v[84:85], v[84:85], s[0:1], v[116:117] op_sel_hi:[1,0,0] neg_lo:[1,0,0] neg_hi:[1,0,0]
	v_pk_mul_f32 v[84:85], v[82:83], v[84:85]
	v_exp_f32_e32 v84, v84
	v_exp_f32_e32 v85, v85
	s_nop 0
	v_pk_add_f32 v[84:85], v[84:85], 1.0 op_sel_hi:[1,0]
	v_rcp_f32_e32 v84, v84
	v_rcp_f32_e32 v85, v85
	s_nop 0
	v_pk_mul_f32 v[82:83], v[82:83], v[84:85]
	v_pk_mul_f32 v[82:83], v[120:121], v[82:83]
	v_cvt_pk_bf16_f32 v81, v82, v83
	v_mov_b64_e32 v[82:83], s[18:19]
	v_mad_i64_i32 v[82:83], s[0:1], v118, s27, v[82:83]
	v_lshl_add_u64 v[82:83], v[176:177], 1, v[82:83]
	global_store_dwordx4 v[82:83], v[78:81], off
; #define PG8_LAS __attribute__((address_space(3)))
;     __device__ __forceinline__ void operator()(const f32x4 (&acc_)[2][2][4][2], const Unit& u, int wr, int wc, int fr, int fq) const {
;     ...
;             for (int m = 0; m < 4; ++m) { const float r = xg[1536 + ai * HALF + wr * 64 + m * 16 + fr];
; #pragma unroll
;                 for (int bj = 0; bj < 2; ++bj)
; #pragma unroll
;                     for (int n = 0; n < 2; ++n) acc[ai][bj][m][n] *= r; }
;         typedef float v2f __attribute__((ext_vector_type(2)));
;         const PG8_LAS float* wl = xg + 1024;
; #pragma unroll
;         for (int ai = 0; ai < 2; ++ai) {
;             const int sp = wr == 1 ? ((ai * 2 + 0) * 2 + 1) : (ai == 1 ? ((0 * 2 + 1) * 2 + 1) : -1);
;             const int sn = wr == 0 ? ((ai * 2 + 1) * 2 + 0) : (ai == 0 ? ((1 * 2 + 0) * 2 + 0) : -1);
; #pragma unroll
;             for (int m = 0; m < 4; ++m) {
;                 const int lr = ai * HALF + wr * 64 + m * 16 + fr, t = a_tok0(u.pm) + lr, tq = t & (Tg - 1);
;                 const float mp = tq == 0 ? 0.f : 1.f, mn = tq == Tg - 1 ? 0.f : 1.f;
;                 u32x4 ov;
; #pragma unroll
;                 for (int n = 0; n < 2; ++n) {
;                     const f32x4 w0 = *(const PG8_LAS f32x4*)(wl + jj + 4 * n), w1 = *(const PG8_LAS f32x4*)(wl + 128 + jj + 4 * n), w2 = *(const PG8_LAS f32x4*)(wl + 256 + jj + 4 * n), bb = *(const PG8_LAS f32x4*)(wl + 384 + jj + 4 * n);
;                     f32x4 bp = {0.f, 0.f, 0.f, 0.f}, bn = {0.f, 0.f, 0.f, 0.f};
;                     if (m == 0 && sp >= 0) bp = *(const PG8_LAS f32x4*)(xg + sp * 128 + jj + 4 * n) * xg[1536 + ai * HALF + wr * 64 - 1];
;                     if (m == 3 && sn >= 0) bn = *(const PG8_LAS f32x4*)(xg + sn * 128 + jj + 4 * n) * xg[1536 + ai * HALF + wr * 64 + 64];
; #pragma unroll
;                     for (int eh = 0; eh < 2; ++eh) { v2f gv, p, q, up;
; #pragma unroll
;                         for (int k = 0; k < 2; ++k) { const int e = 2 * eh + k; const float g0 = acc[ai][0][m][n][e];
;                             const float pa = m > 0 ? dpp_ror1(acc[ai][0][m > 0 ? m - 1 : 0][n][e]) : bp[e];
;                             const float qa = m < 3 ? dpp_ror15(acc[ai][0][m < 3 ? m + 1 : 3][n][e]) : bn[e];
;                             gv[k] = g0; up[k] = acc[ai][1][m][n][e];
.LBB0_671:
	s_or_b64 exec, exec, s[46:47]
	v_pk_mul_f32 v[44:45], v[44:45], v[174:175] op_sel_hi:[1,0]
	v_pk_mul_f32 v[42:43], v[42:43], v[174:175] op_sel_hi:[1,0]
	v_pk_mul_f32 v[40:41], v[40:41], v[174:175] op_sel_hi:[1,0]
	v_pk_mul_f32 v[38:39], v[38:39], v[174:175] op_sel_hi:[1,0]
	v_add_u32_e32 v110, s33, v225
	v_mov_b32_dpp v98, v108 row_ror:1 row_mask:0xf bank_mask:0xf
	v_mov_b32_dpp v100, v42 row_ror:15 row_mask:0xf bank_mask:0xf
	v_mov_b32_dpp v99, v109 row_ror:1 row_mask:0xf bank_mask:0xf
	v_mov_b32_dpp v101, v43 row_ror:15 row_mask:0xf bank_mask:0xf
	v_mov_b32_dpp v94, v106 row_ror:1 row_mask:0xf bank_mask:0xf
	v_mov_b32_dpp v96, v44 row_ror:15 row_mask:0xf bank_mask:0xf
	v_mov_b32_dpp v95, v107 row_ror:1 row_mask:0xf bank_mask:0xf
	v_mov_b32_dpp v97, v45 row_ror:15 row_mask:0xf bank_mask:0xf
	v_mov_b32_dpp v82, v104 row_ror:1 row_mask:0xf bank_mask:0xf
	v_mov_b32_dpp v84, v38 row_ror:15 row_mask:0xf bank_mask:0xf
	v_mov_b32_dpp v83, v105 row_ror:1 row_mask:0xf bank_mask:0xf
	v_mov_b32_dpp v85, v39 row_ror:15 row_mask:0xf bank_mask:0xf
	v_mov_b32_dpp v78, v102 row_ror:1 row_mask:0xf bank_mask:0xf
	v_mov_b32_dpp v80, v40 row_ror:15 row_mask:0xf bank_mask:0xf
	v_mov_b32_dpp v79, v103 row_ror:1 row_mask:0xf bank_mask:0xf
	v_mov_b32_dpp v81, v41 row_ror:15 row_mask:0xf bank_mask:0xf
	v_cmp_gt_i32_e32 vcc, s26, v110
	v_mov_b32_dpp v98, v92 row_shr:1 row_mask:0xf bank_mask:0xf
	v_mov_b32_dpp v100, v92 row_shl:1 row_mask:0xf bank_mask:0xf
	v_mov_b32_dpp v99, v93 row_shr:1 row_mask:0xf bank_mask:0xf
	v_mov_b32_dpp v101, v93 row_shl:1 row_mask:0xf bank_mask:0xf
	v_mov_b32_dpp v94, v90 row_shr:1 row_mask:0xf bank_mask:0xf
	v_mov_b32_dpp v96, v90 row_shl:1 row_mask:0xf bank_mask:0xf
	v_mov_b32_dpp v95, v91 row_shr:1 row_mask:0xf bank_mask:0xf
	v_mov_b32_dpp v97, v91 row_shl:1 row_mask:0xf bank_mask:0xf
	v_mov_b32_dpp v82, v88 row_shr:1 row_mask:0xf bank_mask:0xf
	v_mov_b32_dpp v84, v88 row_shl:1 row_mask:0xf bank_mask:0xf
	v_mov_b32_dpp v83, v89 row_shr:1 row_mask:0xf bank_mask:0xf
	v_mov_b32_dpp v85, v89 row_shl:1 row_mask:0xf bank_mask:0xf
	v_mov_b32_dpp v78, v86 row_shr:1 row_mask:0xf bank_mask:0xf
	v_mov_b32_dpp v80, v86 row_shl:1 row_mask:0xf bank_mask:0xf
	v_mov_b32_dpp v79, v87 row_shr:1 row_mask:0xf bank_mask:0xf
	v_mov_b32_dpp v81, v87 row_shl:1 row_mask:0xf bank_mask:0xf
	s_and_b64 s[0:1], s[36:37], vcc
	s_and_saveexec_b64 s[46:47], s[0:1]
	s_cbranch_execz .LBB0_673
	v_and_b32_e32 v105, s34, v110
	v_cmp_eq_u32_e32 vcc, 0, v105
	v_mov_b32_e32 v178, v179
	v_mov_b32_e32 v102, v179
	v_cndmask_b32_e64 v104, 1.0, 0, vcc
	v_cmp_eq_u32_e32 vcc, s34, v105
	v_mov_b32_e32 v103, v179
	v_pk_mul_f32 v[36:37], v[36:37], v[102:103]
	v_cndmask_b32_e64 v106, 1.0, 0, vcc
	v_pk_mul_f32 v[108:109], v[106:107], v[54:55] op_sel_hi:[0,1]
	v_pk_fma_f32 v[100:101], v[108:109], v[100:101], v[58:59]
	v_pk_mul_f32 v[102:103], v[32:33], v[102:103]
	v_pk_mul_f32 v[32:33], v[30:31], v[178:179]
	v_pk_mul_f32 v[30:31], v[104:105], v[50:51] op_sel_hi:[0,1]
	v_pk_fma_f32 v[100:101], v[92:93], v[46:47], v[100:101]
	s_mov_b32 s0, 0xc0135761
	v_pk_fma_f32 v[30:31], v[30:31], v[98:99], v[100:101]
	v_mov_b64_e32 v[100:101], s[0:1]
	v_pk_mul_f32 v[98:99], v[30:31], v[30:31]
	s_mov_b32 s0, 0x3dd2d3e8
	v_pk_fma_f32 v[98:99], v[98:99], s[0:1], v[100:101] op_sel_hi:[1,0,0] neg_lo:[1,0,0] neg_hi:[1,0,0]
	v_pk_mul_f32 v[34:35], v[34:35], v[178:179]
	v_pk_mul_f32 v[98:99], v[30:31], v[98:99]
	v_exp_f32_e32 v98, v98
	v_exp_f32_e32 v99, v99
	s_nop 0
	v_pk_add_f32 v[98:99], v[98:99], 1.0 op_sel_hi:[1,0]
	v_rcp_f32_e32 v98, v98
	v_rcp_f32_e32 v99, v99
	s_nop 0
	v_pk_mul_f32 v[30:31], v[30:31], v[98:99]
	v_pk_mul_f32 v[98:99], v[106:107], v[56:57] op_sel_hi:[0,1]
	v_pk_fma_f32 v[96:97], v[98:99], v[96:97], v[60:61]
	v_pk_mul_f32 v[30:31], v[34:35], v[30:31]
	v_pk_mul_f32 v[34:35], v[104:105], v[52:53] op_sel_hi:[0,1]
	v_pk_fma_f32 v[96:97], v[90:91], v[48:49], v[96:97]
	v_cvt_pk_bf16_f32 v30, v30, v31
	v_pk_fma_f32 v[34:35], v[34:35], v[94:95], v[96:97]
	v_pk_mul_f32 v[94:95], v[34:35], v[34:35]
	v_pk_fma_f32 v[94:95], v[94:95], s[0:1], v[100:101] op_sel_hi:[1,0,0] neg_lo:[1,0,0] neg_hi:[1,0,0]
	v_pk_mul_f32 v[94:95], v[34:35], v[94:95]
	v_exp_f32_e32 v94, v94
	v_exp_f32_e32 v95, v95
	s_nop 0
	v_pk_add_f32 v[94:95], v[94:95], 1.0 op_sel_hi:[1,0]
	v_rcp_f32_e32 v94, v94
	v_rcp_f32_e32 v95, v95
	s_nop 0
	v_pk_mul_f32 v[34:35], v[34:35], v[94:95]
	v_pk_mul_f32 v[34:35], v[36:37], v[34:35]
	v_pk_mul_f32 v[36:37], v[106:107], v[70:71] op_sel_hi:[0,1]
	v_pk_fma_f32 v[36:37], v[36:37], v[84:85], v[66:67]
	v_cvt_pk_bf16_f32 v31, v34, v35
	v_pk_mul_f32 v[34:35], v[104:105], v[74:75] op_sel_hi:[0,1]
	v_pk_fma_f32 v[36:37], v[88:89], v[62:63], v[36:37]
	v_pk_fma_f32 v[34:35], v[34:35], v[82:83], v[36:37]
	v_pk_mul_f32 v[36:37], v[34:35], v[34:35]
	v_pk_fma_f32 v[36:37], v[36:37], s[0:1], v[100:101] op_sel_hi:[1,0,0] neg_lo:[1,0,0] neg_hi:[1,0,0]
	v_pk_mul_f32 v[36:37], v[34:35], v[36:37]
	v_exp_f32_e32 v36, v36
	v_exp_f32_e32 v37, v37
	s_nop 0
	v_pk_add_f32 v[36:37], v[36:37], 1.0 op_sel_hi:[1,0]
	v_rcp_f32_e32 v36, v36
	v_rcp_f32_e32 v37, v37
	s_nop 0
	v_pk_mul_f32 v[34:35], v[34:35], v[36:37]
	v_pk_mul_f32 v[36:37], v[106:107], v[72:73] op_sel_hi:[0,1]
	v_pk_fma_f32 v[36:37], v[36:37], v[80:81], v[68:69]
	v_pk_mul_f32 v[32:33], v[32:33], v[34:35]
	v_pk_mul_f32 v[34:35], v[104:105], v[76:77] op_sel_hi:[0,1]
	v_pk_fma_f32 v[36:37], v[86:87], v[64:65], v[36:37]
	v_cvt_pk_bf16_f32 v32, v32, v33
	v_pk_fma_f32 v[34:35], v[34:35], v[78:79], v[36:37]
	v_pk_mul_f32 v[36:37], v[34:35], v[34:35]
	v_pk_fma_f32 v[36:37], v[36:37], s[0:1], v[100:101] op_sel_hi:[1,0,0] neg_lo:[1,0,0] neg_hi:[1,0,0]
	v_pk_mul_f32 v[36:37], v[34:35], v[36:37]
	v_exp_f32_e32 v36, v36
	v_exp_f32_e32 v37, v37
	s_nop 0
	v_pk_add_f32 v[36:37], v[36:37], 1.0 op_sel_hi:[1,0]
	v_rcp_f32_e32 v36, v36
	v_rcp_f32_e32 v37, v37
	s_nop 0
	v_pk_mul_f32 v[34:35], v[34:35], v[36:37]
	v_pk_mul_f32 v[34:35], v[102:103], v[34:35]
	v_cvt_pk_bf16_f32 v33, v34, v35
	v_mov_b64_e32 v[34:35], s[18:19]
	v_mad_i64_i32 v[34:35], s[0:1], v110, s27, v[34:35]
	v_lshl_add_u64 v[34:35], v[176:177], 1, v[34:35]
	global_store_dwordx4 v[34:35], v[30:33], off
; #define PG8_LAS __attribute__((address_space(3)))
;     __device__ __forceinline__ void operator()(const f32x4 (&acc_)[2][2][4][2], const Unit& u, int wr, int wc, int fr, int fq) const {
;     ...
;             for (int m = 0; m < 4; ++m) { const float r = xg[1536 + ai * HALF + wr * 64 + m * 16 + fr];
; #pragma unroll
;                 for (int bj = 0; bj < 2; ++bj)
; #pragma unroll
;                     for (int n = 0; n < 2; ++n) acc[ai][bj][m][n] *= r; }
;         typedef float v2f __attribute__((ext_vector_type(2)));
;         const PG8_LAS float* wl = xg + 1024;
; #pragma unroll
;         for (int ai = 0; ai < 2; ++ai) {
;             const int sp = wr == 1 ? ((ai * 2 + 0) * 2 + 1) : (ai == 1 ? ((0 * 2 + 1) * 2 + 1) : -1);
;             const int sn = wr == 0 ? ((ai * 2 + 1) * 2 + 0) : (ai == 0 ? ((1 * 2 + 0) * 2 + 0) : -1);
; #pragma unroll
;             for (int m = 0; m < 4; ++m) {
;                 const int lr = ai * HALF + wr * 64 + m * 16 + fr, t = a_tok0(u.pm) + lr, tq = t & (Tg - 1);
;                 const float mp = tq == 0 ? 0.f : 1.f, mn = tq == Tg - 1 ? 0.f : 1.f;
;                 u32x4 ov;
; #pragma unroll
;                 for (int n = 0; n < 2; ++n) {
;                     const f32x4 w0 = *(const PG8_LAS f32x4*)(wl + jj + 4 * n), w1 = *(const PG8_LAS f32x4*)(wl + 128 + jj + 4 * n), w2 = *(const PG8_LAS f32x4*)(wl + 256 + jj + 4 * n), bb = *(const PG8_LAS f32x4*)(wl + 384 + jj + 4 * n);
;                     f32x4 bp = {0.f, 0.f, 0.f, 0.f}, bn = {0.f, 0.f, 0.f, 0.f};
;                     if (m == 0 && sp >= 0) bp = *(const PG8_LAS f32x4*)(xg + sp * 128 + jj + 4 * n) * xg[1536 + ai * HALF + wr * 64 - 1];
;                     if (m == 3 && sn >= 0) bn = *(const PG8_LAS f32x4*)(xg + sn * 128 + jj + 4 * n) * xg[1536 + ai * HALF + wr * 64 + 64];
; #pragma unroll
;                     for (int eh = 0; eh < 2; ++eh) { v2f gv, p, q, up;
; #pragma unroll
;                         for (int k = 0; k < 2; ++k) { const int e = 2 * eh + k; const float g0 = acc[ai][0][m][n][e];
;                             const float pa = m > 0 ? dpp_ror1(acc[ai][0][m > 0 ? m - 1 : 0][n][e]) : bp[e];
;                             const float qa = m < 3 ? dpp_ror15(acc[ai][0][m < 3 ? m + 1 : 3][n][e]) : bn[e];
;                             gv[k] = g0; up[k] = acc[ai][1][m][n][e];
.LBB0_673:
	s_or_b64 exec, exec, s[46:47]
	s_nop 0
	v_mov_b32_e32 v30, v175
	v_pk_mul_f32 v[28:29], v[28:29], v[30:31] op_sel_hi:[1,0]
	v_pk_mul_f32 v[26:27], v[26:27], v[30:31] op_sel_hi:[1,0]
	v_pk_mul_f32 v[24:25], v[24:25], v[30:31] op_sel_hi:[1,0]
	v_pk_mul_f32 v[22:23], v[22:23], v[30:31] op_sel_hi:[1,0]
	v_add_u32_e32 v94, s33, v226
	v_mov_b32_dpp v82, v92 row_ror:1 row_mask:0xf bank_mask:0xf
	v_mov_b32_dpp v84, v26 row_ror:15 row_mask:0xf bank_mask:0xf
	v_mov_b32_dpp v83, v93 row_ror:1 row_mask:0xf bank_mask:0xf
	v_mov_b32_dpp v85, v27 row_ror:15 row_mask:0xf bank_mask:0xf
	v_mov_b32_dpp v78, v90 row_ror:1 row_mask:0xf bank_mask:0xf
	v_mov_b32_dpp v80, v28 row_ror:15 row_mask:0xf bank_mask:0xf
	v_mov_b32_dpp v79, v91 row_ror:1 row_mask:0xf bank_mask:0xf
	v_mov_b32_dpp v81, v29 row_ror:15 row_mask:0xf bank_mask:0xf
	v_mov_b32_dpp v34, v88 row_ror:1 row_mask:0xf bank_mask:0xf
	v_mov_b32_dpp v36, v22 row_ror:15 row_mask:0xf bank_mask:0xf
	v_mov_b32_dpp v35, v89 row_ror:1 row_mask:0xf bank_mask:0xf
	v_mov_b32_dpp v37, v23 row_ror:15 row_mask:0xf bank_mask:0xf
	v_mov_b32_dpp v30, v86 row_ror:1 row_mask:0xf bank_mask:0xf
	v_mov_b32_dpp v32, v24 row_ror:15 row_mask:0xf bank_mask:0xf
	v_mov_b32_dpp v31, v87 row_ror:1 row_mask:0xf bank_mask:0xf
	v_mov_b32_dpp v33, v25 row_ror:15 row_mask:0xf bank_mask:0xf
	v_cmp_gt_i32_e32 vcc, s26, v94
	v_mov_b32_dpp v82, v42 row_shr:1 row_mask:0xf bank_mask:0xf
	v_mov_b32_dpp v84, v42 row_shl:1 row_mask:0xf bank_mask:0xf
	v_mov_b32_dpp v83, v43 row_shr:1 row_mask:0xf bank_mask:0xf
	v_mov_b32_dpp v85, v43 row_shl:1 row_mask:0xf bank_mask:0xf
	v_mov_b32_dpp v78, v44 row_shr:1 row_mask:0xf bank_mask:0xf
	v_mov_b32_dpp v80, v44 row_shl:1 row_mask:0xf bank_mask:0xf
	v_mov_b32_dpp v79, v45 row_shr:1 row_mask:0xf bank_mask:0xf
	v_mov_b32_dpp v81, v45 row_shl:1 row_mask:0xf bank_mask:0xf
	v_mov_b32_dpp v34, v38 row_shr:1 row_mask:0xf bank_mask:0xf
	v_mov_b32_dpp v36, v38 row_shl:1 row_mask:0xf bank_mask:0xf
	v_mov_b32_dpp v35, v39 row_shr:1 row_mask:0xf bank_mask:0xf
	v_mov_b32_dpp v37, v39 row_shl:1 row_mask:0xf bank_mask:0xf
	v_mov_b32_dpp v30, v40 row_shr:1 row_mask:0xf bank_mask:0xf
	v_mov_b32_dpp v32, v40 row_shl:1 row_mask:0xf bank_mask:0xf
	v_mov_b32_dpp v31, v41 row_shr:1 row_mask:0xf bank_mask:0xf
	v_mov_b32_dpp v33, v41 row_shl:1 row_mask:0xf bank_mask:0xf
	s_and_b64 s[0:1], s[38:39], vcc
	s_and_saveexec_b64 s[46:47], s[0:1]
	s_cbranch_execz .LBB0_675
	v_mov_b32_e32 v86, v174
	v_mov_b32_e32 v87, v174
	v_mov_b32_e32 v88, v174
	v_mov_b32_e32 v89, v174
	v_pk_mul_f32 v[20:21], v[20:21], v[88:89]
	v_pk_mul_f32 v[18:19], v[18:19], v[86:87]
	v_pk_mul_f32 v[88:89], v[16:17], v[88:89]
	v_pk_mul_f32 v[16:17], v[14:15], v[86:87]
	v_and_b32_e32 v87, s34, v94
	v_cmp_eq_u32_e32 vcc, 0, v87
	s_mov_b32 s0, 0xc0135761
	s_nop 0
	v_cndmask_b32_e64 v86, 1.0, 0, vcc
	v_cmp_eq_u32_e32 vcc, s34, v87
	v_pk_mul_f32 v[14:15], v[86:87], v[50:51] op_sel_hi:[0,1]
	s_nop 0
	v_cndmask_b32_e64 v90, 1.0, 0, vcc
	v_pk_mul_f32 v[92:93], v[90:91], v[54:55] op_sel_hi:[0,1]
	v_pk_fma_f32 v[84:85], v[92:93], v[84:85], v[58:59]
	v_pk_fma_f32 v[84:85], v[42:43], v[46:47], v[84:85]
	v_pk_fma_f32 v[14:15], v[14:15], v[82:83], v[84:85]
	v_mov_b64_e32 v[84:85], s[0:1]
	v_pk_mul_f32 v[82:83], v[14:15], v[14:15]
	s_mov_b32 s0, 0x3dd2d3e8
	v_pk_fma_f32 v[82:83], v[82:83], s[0:1], v[84:85] op_sel_hi:[1,0,0] neg_lo:[1,0,0] neg_hi:[1,0,0]
	v_pk_mul_f32 v[82:83], v[14:15], v[82:83]
	v_exp_f32_e32 v82, v82
	v_exp_f32_e32 v83, v83
	s_nop 0
	v_pk_add_f32 v[82:83], v[82:83], 1.0 op_sel_hi:[1,0]
	v_rcp_f32_e32 v82, v82
	v_rcp_f32_e32 v83, v83
	s_nop 0
	v_pk_mul_f32 v[14:15], v[14:15], v[82:83]
	v_pk_mul_f32 v[82:83], v[90:91], v[56:57] op_sel_hi:[0,1]
	v_pk_fma_f32 v[80:81], v[82:83], v[80:81], v[60:61]
	v_pk_mul_f32 v[14:15], v[18:19], v[14:15]
	v_pk_mul_f32 v[18:19], v[86:87], v[52:53] op_sel_hi:[0,1]
	v_pk_fma_f32 v[80:81], v[44:45], v[48:49], v[80:81]
	v_cvt_pk_bf16_f32 v14, v14, v15
	v_pk_fma_f32 v[18:19], v[18:19], v[78:79], v[80:81]
	v_pk_mul_f32 v[78:79], v[18:19], v[18:19]
	v_pk_fma_f32 v[78:79], v[78:79], s[0:1], v[84:85] op_sel_hi:[1,0,0] neg_lo:[1,0,0] neg_hi:[1,0,0]
	v_pk_mul_f32 v[78:79], v[18:19], v[78:79]
	v_exp_f32_e32 v78, v78
	v_exp_f32_e32 v79, v79
	s_nop 0
	v_pk_add_f32 v[78:79], v[78:79], 1.0 op_sel_hi:[1,0]
	v_rcp_f32_e32 v78, v78
	v_rcp_f32_e32 v79, v79
	s_nop 0
	v_pk_mul_f32 v[18:19], v[18:19], v[78:79]
	v_pk_mul_f32 v[18:19], v[20:21], v[18:19]
	v_pk_mul_f32 v[20:21], v[90:91], v[70:71] op_sel_hi:[0,1]
	v_pk_fma_f32 v[20:21], v[20:21], v[36:37], v[66:67]
	v_cvt_pk_bf16_f32 v15, v18, v19
	v_pk_mul_f32 v[18:19], v[86:87], v[74:75] op_sel_hi:[0,1]
	v_pk_fma_f32 v[20:21], v[38:39], v[62:63], v[20:21]
	v_pk_fma_f32 v[18:19], v[18:19], v[34:35], v[20:21]
	v_pk_mul_f32 v[20:21], v[18:19], v[18:19]
	v_pk_fma_f32 v[20:21], v[20:21], s[0:1], v[84:85] op_sel_hi:[1,0,0] neg_lo:[1,0,0] neg_hi:[1,0,0]
	v_pk_mul_f32 v[20:21], v[18:19], v[20:21]
	v_exp_f32_e32 v20, v20
	v_exp_f32_e32 v21, v21
	s_nop 0
	v_pk_add_f32 v[20:21], v[20:21], 1.0 op_sel_hi:[1,0]
	v_rcp_f32_e32 v20, v20
	v_rcp_f32_e32 v21, v21
	s_nop 0
	v_pk_mul_f32 v[18:19], v[18:19], v[20:21]
	v_pk_mul_f32 v[20:21], v[90:91], v[72:73] op_sel_hi:[0,1]
	v_pk_fma_f32 v[20:21], v[20:21], v[32:33], v[68:69]
	v_pk_mul_f32 v[16:17], v[16:17], v[18:19]
	v_pk_mul_f32 v[18:19], v[86:87], v[76:77] op_sel_hi:[0,1]
	v_pk_fma_f32 v[20:21], v[40:41], v[64:65], v[20:21]
	v_cvt_pk_bf16_f32 v16, v16, v17
	v_pk_fma_f32 v[18:19], v[18:19], v[30:31], v[20:21]
	v_pk_mul_f32 v[20:21], v[18:19], v[18:19]
	v_pk_fma_f32 v[20:21], v[20:21], s[0:1], v[84:85] op_sel_hi:[1,0,0] neg_lo:[1,0,0] neg_hi:[1,0,0]
	v_pk_mul_f32 v[20:21], v[18:19], v[20:21]
	v_exp_f32_e32 v20, v20
	v_exp_f32_e32 v21, v21
	s_nop 0
	v_pk_add_f32 v[20:21], v[20:21], 1.0 op_sel_hi:[1,0]
	v_rcp_f32_e32 v20, v20
	v_rcp_f32_e32 v21, v21
	s_nop 0
	v_pk_mul_f32 v[18:19], v[18:19], v[20:21]
	v_pk_mul_f32 v[18:19], v[88:89], v[18:19]
	v_cvt_pk_bf16_f32 v17, v18, v19
	v_mov_b64_e32 v[18:19], s[18:19]
	v_mad_i64_i32 v[18:19], s[0:1], v94, s27, v[18:19]
	v_lshl_add_u64 v[18:19], v[176:177], 1, v[18:19]
	global_store_dwordx4 v[18:19], v[14:17], off

;     __device__ __forceinline__ void operator()(const f32x4 (&acc_)[2][2][4][2], const Unit& u, int wr, int wc, int fr, int fq) const {
;     ...
;                 const int lr = ai * HALF + wr * 64 + m * 16 + fr, t = a_tok0(u.pm) + lr, tq = t & (Tg - 1);
;                 const float mp = tq == 0 ? 0.f : 1.f, mn = tq == Tg - 1 ? 0.f : 1.f;
;                 u32x4 ov;
; #pragma unroll
;                 for (int n = 0; n < 2; ++n) {
;                     const f32x4 w0 = *(const PG8_LAS f32x4*)(wl + jj + 4 * n), w1 = *(const PG8_LAS f32x4*)(wl + 128 + jj + 4 * n), w2 = *(const PG8_LAS f32x4*)(wl + 256 + jj + 4 * n), bb = *(const PG8_LAS f32x4*)(wl + 384 + jj + 4 * n);
;                     f32x4 bp = {0.f, 0.f, 0.f, 0.f}, bn = {0.f, 0.f, 0.f, 0.f};
;                     if (m == 0 && sp >= 0) bp = *(const PG8_LAS f32x4*)(xg + sp * 128 + jj + 4 * n) * xg[1536 + ai * HALF + wr * 64 - 1];
;                     if (m == 3 && sn >= 0) bn = *(const PG8_LAS f32x4*)(xg + sn * 128 + jj + 4 * n) * xg[1536 + ai * HALF + wr * 64 + 64];
; #pragma unroll
;                     for (int eh = 0; eh < 2; ++eh) { v2f gv, p, q, up;
; #pragma unroll
;                         for (int k = 0; k < 2; ++k) { const int e = 2 * eh + k; const float g0 = acc[ai][0][m][n][e];
;                             const float pa = m > 0 ? dpp_ror1(acc[ai][0][m > 0 ? m - 1 : 0][n][e]) : bp[e];
;                             const float qa = m < 3 ? dpp_ror15(acc[ai][0][m < 3 ? m + 1 : 3][n][e]) : bn[e];
;                             gv[k] = g0; up[k] = acc[ai][1][m][n][e];
;                             p[k] = __builtin_bit_cast(float, __builtin_amdgcn_update_dpp(__builtin_bit_cast(int, pa), __builtin_bit_cast(int, g0), 0x111, 0xf, 0xf, false));
;                             q[k] = __builtin_bit_cast(float, __builtin_amdgcn_update_dpp(__builtin_bit_cast(int, qa), __builtin_bit_cast(int, g0), 0x101, 0xf, 0xf, false)); }
;                         const v2f a0 = (v2f){w0[2 * eh], w0[2 * eh + 1]} * mp, a1 = (v2f){w1[2 * eh], w1[2 * eh + 1]}, a2 = (v2f){w2[2 * eh], w2[2 * eh + 1]} * mn, ab = (v2f){bb[2 * eh], bb[2 * eh + 1]};
;                         const v2f x = a0 * p + (a1 * gv + (a2 * q + ab));
;                         const v2f arg = x * ((x * x) * (-0.10294324f) + (-2.3022082f));
;                         v2f ex; ex[0] = __builtin_amdgcn_exp2f(arg[0]); ex[1] = __builtin_amdgcn_exp2f(arg[1]);
.LBB0_679:
	v_add_u32_e32 v42, s33, v227
	v_mov_b32_dpp v34, v38 row_ror:1 row_mask:0xf bank_mask:0xf
	v_mov_b32_dpp v35, v39 row_ror:1 row_mask:0xf bank_mask:0xf
	v_mov_b32_dpp v20, v40 row_ror:1 row_mask:0xf bank_mask:0xf
	v_mov_b32_dpp v21, v41 row_ror:1 row_mask:0xf bank_mask:0xf
	v_cmp_gt_i32_e32 vcc, s26, v42
	v_mov_b32_dpp v34, v22 row_shr:1 row_mask:0xf bank_mask:0xf
	v_mov_b32_dpp v14, v22 row_shl:1 row_mask:0xf bank_mask:0xf
	v_mov_b32_dpp v35, v23 row_shr:1 row_mask:0xf bank_mask:0xf
	v_mov_b32_dpp v15, v23 row_shl:1 row_mask:0xf bank_mask:0xf
	v_mov_b32_dpp v20, v24 row_shr:1 row_mask:0xf bank_mask:0xf
	v_mov_b32_dpp v16, v24 row_shl:1 row_mask:0xf bank_mask:0xf
	v_mov_b32_dpp v21, v25 row_shr:1 row_mask:0xf bank_mask:0xf
	v_mov_b32_dpp v17, v25 row_shl:1 row_mask:0xf bank_mask:0xf
	s_and_b64 s[0:1], s[40:41], vcc
	s_and_saveexec_b64 s[46:47], s[0:1]
	s_cbranch_execz .LBB0_681
	v_and_b32_e32 v39, s34, v42
	v_cmp_eq_u32_e32 vcc, 0, v39
	s_mov_b32 s0, 0xc0135761
	v_mov_b32_e32 v44, v175
	v_cndmask_b32_e64 v38, 1.0, 0, vcc
	v_cmp_eq_u32_e32 vcc, s34, v39
	v_pk_mul_f32 v[50:51], v[38:39], v[50:51] op_sel_hi:[0,1]
	v_mov_b32_e32 v45, v175
	v_cndmask_b32_e64 v40, 1.0, 0, vcc
	v_pk_mul_f32 v[54:55], v[40:41], v[54:55] op_sel_hi:[0,1]
	v_pk_fma_f32 v[32:33], v[54:55], v[32:33], v[58:59]
	v_mov_b32_e32 v174, v175
	v_pk_fma_f32 v[26:27], v[46:47], v[26:27], v[32:33]
	v_pk_mul_f32 v[46:47], v[38:39], v[52:53] op_sel_hi:[0,1]
	v_pk_fma_f32 v[26:27], v[50:51], v[36:37], v[26:27]
	v_pk_mul_f32 v[50:51], v[40:41], v[56:57] op_sel_hi:[0,1]
	v_pk_fma_f32 v[18:19], v[50:51], v[18:19], v[60:61]
	v_mov_b64_e32 v[36:37], s[0:1]
	v_pk_fma_f32 v[18:19], v[48:49], v[28:29], v[18:19]
	s_mov_b32 s0, 0x3dd2d3e8
	v_pk_fma_f32 v[18:19], v[46:47], v[30:31], v[18:19]
	v_pk_mul_f32 v[32:33], v[26:27], v[26:27]
	v_pk_mul_f32 v[28:29], v[18:19], v[18:19]
	v_pk_fma_f32 v[32:33], v[32:33], s[0:1], v[36:37] op_sel_hi:[1,0,0] neg_lo:[1,0,0] neg_hi:[1,0,0]
	v_pk_fma_f32 v[28:29], v[28:29], s[0:1], v[36:37] op_sel_hi:[1,0,0] neg_lo:[1,0,0] neg_hi:[1,0,0]
	v_pk_mul_f32 v[32:33], v[26:27], v[32:33]
	v_pk_mul_f32 v[28:29], v[18:19], v[28:29]
	v_exp_f32_e32 v32, v32
	v_exp_f32_e32 v28, v28
	v_exp_f32_e32 v29, v29
	v_exp_f32_e32 v33, v33
	v_pk_mul_f32 v[12:13], v[12:13], v[44:45]
	v_pk_mul_f32 v[10:11], v[10:11], v[174:175]
	v_pk_add_f32 v[28:29], v[28:29], 1.0 op_sel_hi:[1,0]
	v_pk_add_f32 v[30:31], v[32:33], 1.0 op_sel_hi:[1,0]
	v_rcp_f32_e32 v28, v28
	v_rcp_f32_e32 v29, v29
	v_rcp_f32_e32 v30, v30
	v_rcp_f32_e32 v31, v31
	v_pk_mul_f32 v[6:7], v[6:7], v[174:175]
	v_pk_mul_f32 v[18:19], v[18:19], v[28:29]
	v_pk_mul_f32 v[8:9], v[8:9], v[44:45]
	v_pk_mul_f32 v[26:27], v[26:27], v[30:31]
	v_pk_mul_f32 v[12:13], v[12:13], v[18:19]
	v_pk_mul_f32 v[18:19], v[40:41], v[70:71] op_sel_hi:[0,1]
	v_pk_mul_f32 v[10:11], v[10:11], v[26:27]
	v_pk_fma_f32 v[14:15], v[18:19], v[14:15], v[66:67]
	v_cvt_pk_bf16_f32 v10, v10, v11
	v_cvt_pk_bf16_f32 v11, v12, v13
	v_pk_mul_f32 v[12:13], v[38:39], v[74:75] op_sel_hi:[0,1]
	v_pk_fma_f32 v[14:15], v[22:23], v[62:63], v[14:15]
	v_pk_mul_f32 v[22:23], v[40:41], v[72:73] op_sel_hi:[0,1]
	v_pk_fma_f32 v[12:13], v[12:13], v[34:35], v[14:15]
	v_pk_fma_f32 v[16:17], v[22:23], v[16:17], v[68:69]
	v_pk_mul_f32 v[14:15], v[12:13], v[12:13]
	v_pk_mul_f32 v[18:19], v[38:39], v[76:77] op_sel_hi:[0,1]
	v_pk_fma_f32 v[16:17], v[24:25], v[64:65], v[16:17]
	v_pk_fma_f32 v[14:15], v[14:15], s[0:1], v[36:37] op_sel_hi:[1,0,0] neg_lo:[1,0,0] neg_hi:[1,0,0]
	v_pk_fma_f32 v[16:17], v[18:19], v[20:21], v[16:17]
	v_pk_mul_f32 v[14:15], v[12:13], v[14:15]
	v_pk_mul_f32 v[18:19], v[16:17], v[16:17]
	v_exp_f32_e32 v14, v14
	v_exp_f32_e32 v15, v15
	v_pk_fma_f32 v[18:19], v[18:19], s[0:1], v[36:37] op_sel_hi:[1,0,0] neg_lo:[1,0,0] neg_hi:[1,0,0]
	v_pk_add_f32 v[14:15], v[14:15], 1.0 op_sel_hi:[1,0]
	v_pk_mul_f32 v[18:19], v[16:17], v[18:19]
	v_rcp_f32_e32 v14, v14
	v_exp_f32_e32 v18, v18
	v_exp_f32_e32 v19, v19
	v_rcp_f32_e32 v15, v15
	v_pk_add_f32 v[18:19], v[18:19], 1.0 op_sel_hi:[1,0]
	v_rcp_f32_e32 v18, v18
	v_rcp_f32_e32 v19, v19
	v_pk_mul_f32 v[12:13], v[12:13], v[14:15]
	v_pk_mul_f32 v[6:7], v[6:7], v[12:13]
	v_cvt_pk_bf16_f32 v12, v6, v7
	v_pk_mul_f32 v[6:7], v[16:17], v[18:19]
	v_pk_mul_f32 v[6:7], v[8:9], v[6:7]
	v_cvt_pk_bf16_f32 v13, v6, v7
	v_mov_b64_e32 v[6:7], s[18:19]
	v_mad_i64_i32 v[6:7], s[0:1], v42, s27, v[6:7]
	v_lshl_add_u64 v[6:7], v[176:177], 1, v[6:7]
	global_store_dwordx4 v[6:7], v[10:13], off
